# FFN-up epilogue: select + row_ror replaces the four shifted DPP taps per value (2 cndmask + 2 DPP)
# baseline (speedup 1.0000x reference)
.Lst_out_s3:
	s_lshl_b32 s8, s0, 8
	s_add_i32 s8, s8, s56
	s_lshl_b32 s9, s1, 7
	s_add_i32 s9, s9, s49
	s_lshl_b32 s10, s0, 3
	s_lshr_b32 s11, s56, 5
	s_add_i32 s10, s10, s11
	v_add_u32_e32 v200, s8, v163
	v_lshlrev_b32_e32 v213, 2, v200
	global_load_dword v188, v213, s[12:13]
	global_load_dword v189, v213, s[12:13] offset:64
	global_load_dword v190, v213, s[12:13] offset:128
	global_load_dword v191, v213, s[12:13] offset:192
	global_load_dword v192, v213, s[12:13] offset:256
	global_load_dword v193, v213, s[12:13] offset:320
	global_load_dword v194, v213, s[12:13] offset:384
	global_load_dword v195, v213, s[12:13] offset:448
	v_lshl_add_u32 v201, v225, 3, s9
	v_lshlrev_b32_e32 v212, 2, v201
	global_load_dwordx4 v[76:79], v212, s[82:83]
	v_add_u32_e32 v213, 0xb000, v212
	global_load_dwordx4 v[80:83], v213, s[82:83]
	v_add_u32_e32 v213, 0x16000, v212
	global_load_dwordx4 v[84:87], v213, s[82:83]
	global_load_dwordx4 v[88:91], v212, s[84:85]
	v_add_u32_e32 v213, 0x5800, v212
	global_load_dwordx4 v[92:95], v213, s[82:83]
	v_add_u32_e32 v213, 0x10800, v212
	global_load_dwordx4 v[96:99], v213, s[82:83]
	v_add_u32_e32 v213, 0x1b800, v212
	global_load_dwordx4 v[100:103], v213, s[82:83]
	v_add_u32_e32 v213, 0x5800, v212
	global_load_dwordx4 v[104:107], v213, s[84:85]
	v_mul_u32_u24_e32 v215, 0x2c00, v200
	v_lshl_add_u32 v215, v201, 1, v215
	v_add_u32_e32 v213, s10, v163
	v_mul_u32_u24_e32 v217, 0xb000, v213
	v_add_u32_e32 v217, v217, v212
	v_cmp_gt_u32_e64 s[8:9], 2, v163
	v_cmp_lt_u32_e64 s[10:11], 13, v163
	v_cmp_lt_u32_e32 vcc, 1, v163
	v_mov_b32_e32 v214, 1.0
	v_mov_b32_e32 v216, 0xbfb8aa3b
	v_mov_b32_e32 v108, 0x3727c5ac
	s_waitcnt vmcnt(8)
	v_fmamk_f32 v188, v188, 0x3a000000, v108
	v_fmamk_f32 v189, v189, 0x3a000000, v108
	v_fmamk_f32 v190, v190, 0x3a000000, v108
	v_fmamk_f32 v191, v191, 0x3a000000, v108
	v_fmamk_f32 v192, v192, 0x3a000000, v108
	v_fmamk_f32 v193, v193, 0x3a000000, v108
	v_fmamk_f32 v194, v194, 0x3a000000, v108
	v_fmamk_f32 v195, v195, 0x3a000000, v108
	v_rsq_f32_e32 v188, v188
	v_rsq_f32_e32 v189, v189
	v_rsq_f32_e32 v190, v190
	v_rsq_f32_e32 v191, v191
	v_rsq_f32_e32 v192, v192
	v_rsq_f32_e32 v193, v193
	v_rsq_f32_e32 v194, v194
	v_rsq_f32_e32 v195, v195
	v_pk_mul_f32 v[158:159], v[158:159], v[188:189] op_sel_hi:[1,0]
	v_pk_mul_f32 v[160:161], v[160:161], v[188:189] op_sel_hi:[1,0]
	v_pk_mul_f32 v[60:61], v[60:61], v[188:189] op_sel_hi:[1,0]
	v_pk_mul_f32 v[62:63], v[62:63], v[188:189] op_sel_hi:[1,0]
	v_pk_mul_f32 v[154:155], v[154:155], v[188:189] op_sel_hi:[1,0]
	v_pk_mul_f32 v[156:157], v[156:157], v[188:189] op_sel_hi:[1,0]
	v_pk_mul_f32 v[56:57], v[56:57], v[188:189] op_sel_hi:[1,0]
	v_pk_mul_f32 v[58:59], v[58:59], v[188:189] op_sel_hi:[1,0]
	v_pk_mul_f32 v[150:151], v[150:151], v[188:189] op_sel:[0,1] op_sel_hi:[1,1]
	v_pk_mul_f32 v[152:153], v[152:153], v[188:189] op_sel:[0,1] op_sel_hi:[1,1]
	v_pk_mul_f32 v[52:53], v[52:53], v[188:189] op_sel:[0,1] op_sel_hi:[1,1]
	v_pk_mul_f32 v[54:55], v[54:55], v[188:189] op_sel:[0,1] op_sel_hi:[1,1]
	v_pk_mul_f32 v[142:143], v[142:143], v[188:189] op_sel:[0,1] op_sel_hi:[1,1]
	v_pk_mul_f32 v[144:145], v[144:145], v[188:189] op_sel:[0,1] op_sel_hi:[1,1]
	v_pk_mul_f32 v[44:45], v[44:45], v[188:189] op_sel:[0,1] op_sel_hi:[1,1]
	v_pk_mul_f32 v[46:47], v[46:47], v[188:189] op_sel:[0,1] op_sel_hi:[1,1]
	v_pk_mul_f32 v[146:147], v[146:147], v[190:191] op_sel_hi:[1,0]
	v_pk_mul_f32 v[148:149], v[148:149], v[190:191] op_sel_hi:[1,0]
	v_pk_mul_f32 v[48:49], v[48:49], v[190:191] op_sel_hi:[1,0]
	v_pk_mul_f32 v[50:51], v[50:51], v[190:191] op_sel_hi:[1,0]
	v_pk_mul_f32 v[134:135], v[134:135], v[190:191] op_sel_hi:[1,0]
	v_pk_mul_f32 v[136:137], v[136:137], v[190:191] op_sel_hi:[1,0]
	v_pk_mul_f32 v[36:37], v[36:37], v[190:191] op_sel_hi:[1,0]
	v_pk_mul_f32 v[38:39], v[38:39], v[190:191] op_sel_hi:[1,0]
	v_pk_mul_f32 v[138:139], v[138:139], v[190:191] op_sel:[0,1] op_sel_hi:[1,1]
	v_pk_mul_f32 v[140:141], v[140:141], v[190:191] op_sel:[0,1] op_sel_hi:[1,1]
	v_pk_mul_f32 v[40:41], v[40:41], v[190:191] op_sel:[0,1] op_sel_hi:[1,1]
	v_pk_mul_f32 v[42:43], v[42:43], v[190:191] op_sel:[0,1] op_sel_hi:[1,1]
	v_pk_mul_f32 v[130:131], v[130:131], v[190:191] op_sel:[0,1] op_sel_hi:[1,1]
	v_pk_mul_f32 v[132:133], v[132:133], v[190:191] op_sel:[0,1] op_sel_hi:[1,1]
	v_pk_mul_f32 v[32:33], v[32:33], v[190:191] op_sel:[0,1] op_sel_hi:[1,1]
	v_pk_mul_f32 v[34:35], v[34:35], v[190:191] op_sel:[0,1] op_sel_hi:[1,1]
	v_pk_mul_f32 v[126:127], v[126:127], v[192:193] op_sel_hi:[1,0]
	v_pk_mul_f32 v[128:129], v[128:129], v[192:193] op_sel_hi:[1,0]
	v_pk_mul_f32 v[28:29], v[28:29], v[192:193] op_sel_hi:[1,0]
	v_pk_mul_f32 v[30:31], v[30:31], v[192:193] op_sel_hi:[1,0]
	v_pk_mul_f32 v[118:119], v[118:119], v[192:193] op_sel_hi:[1,0]
	v_pk_mul_f32 v[120:121], v[120:121], v[192:193] op_sel_hi:[1,0]
	v_pk_mul_f32 v[16:17], v[16:17], v[192:193] op_sel_hi:[1,0]
	v_pk_mul_f32 v[18:19], v[18:19], v[192:193] op_sel_hi:[1,0]
	v_pk_mul_f32 v[122:123], v[122:123], v[192:193] op_sel:[0,1] op_sel_hi:[1,1]
	v_pk_mul_f32 v[124:125], v[124:125], v[192:193] op_sel:[0,1] op_sel_hi:[1,1]
	v_pk_mul_f32 v[24:25], v[24:25], v[192:193] op_sel:[0,1] op_sel_hi:[1,1]
	v_pk_mul_f32 v[26:27], v[26:27], v[192:193] op_sel:[0,1] op_sel_hi:[1,1]
	v_pk_mul_f32 v[110:111], v[110:111], v[192:193] op_sel:[0,1] op_sel_hi:[1,1]
	v_pk_mul_f32 v[112:113], v[112:113], v[192:193] op_sel:[0,1] op_sel_hi:[1,1]
	v_pk_mul_f32 v[12:13], v[12:13], v[192:193] op_sel:[0,1] op_sel_hi:[1,1]
	v_pk_mul_f32 v[14:15], v[14:15], v[192:193] op_sel:[0,1] op_sel_hi:[1,1]
	v_pk_mul_f32 v[114:115], v[114:115], v[194:195] op_sel_hi:[1,0]
	v_pk_mul_f32 v[116:117], v[116:117], v[194:195] op_sel_hi:[1,0]
	v_pk_mul_f32 v[20:21], v[20:21], v[194:195] op_sel_hi:[1,0]
	v_pk_mul_f32 v[22:23], v[22:23], v[194:195] op_sel_hi:[1,0]
	v_pk_mul_f32 v[68:69], v[68:69], v[194:195] op_sel_hi:[1,0]
	v_pk_mul_f32 v[70:71], v[70:71], v[194:195] op_sel_hi:[1,0]
	v_pk_mul_f32 v[8:9], v[8:9], v[194:195] op_sel_hi:[1,0]
	v_pk_mul_f32 v[10:11], v[10:11], v[194:195] op_sel_hi:[1,0]
	v_pk_mul_f32 v[72:73], v[72:73], v[194:195] op_sel:[0,1] op_sel_hi:[1,1]
	v_pk_mul_f32 v[74:75], v[74:75], v[194:195] op_sel:[0,1] op_sel_hi:[1,1]
	v_pk_mul_f32 v[4:5], v[4:5], v[194:195] op_sel:[0,1] op_sel_hi:[1,1]
	v_pk_mul_f32 v[6:7], v[6:7], v[194:195] op_sel:[0,1] op_sel_hi:[1,1]
	v_pk_mul_f32 v[64:65], v[64:65], v[194:195] op_sel:[0,1] op_sel_hi:[1,1]
	v_pk_mul_f32 v[66:67], v[66:67], v[194:195] op_sel:[0,1] op_sel_hi:[1,1]
	v_pk_mul_f32 v[0:1], v[0:1], v[194:195] op_sel:[0,1] op_sel_hi:[1,1]
	v_pk_mul_f32 v[2:3], v[2:3], v[194:195] op_sel:[0,1] op_sel_hi:[1,1]
	s_nop 1
	s_mov_b64 exec, s[8:9]
	v_add_u32_e32 v213, 0x5800, v217
	global_store_dwordx4 v217, v[158:161], s[70:71]
	global_store_dwordx4 v213, v[154:157], s[70:71]
	global_store_dwordx4 v217, v[60:63], s[70:71] offset:16
	global_store_dwordx4 v213, v[56:59], s[70:71] offset:16
	s_mov_b64 exec, s[10:11]
	v_add_u32_e32 v213, 0xfff7c000, v217
	global_store_dwordx4 v213, v[72:75], s[70:71]
	global_store_dwordx4 v213, v[4:7], s[70:71] offset:16
	v_add_u32_e32 v213, 0xfff81800, v217
	global_store_dwordx4 v213, v[64:67], s[70:71]
	global_store_dwordx4 v213, v[0:3], s[70:71] offset:16
	s_mov_b64 exec, -1
	v_cmp_eq_u32_e64 s[8:9], 15, v163
	v_add_u32_e32 v213, 0x1b800, v212
	global_load_dwordx4 v[204:207], v213, s[82:83] offset:16
	v_add_u32_e32 v213, 0x5800, v212
	global_load_dwordx4 v[208:211], v213, s[84:85] offset:16
	s_waitcnt vmcnt(10)
	v_pk_fma_f32 v[188:189], v[158:159], v[84:85], v[88:89]
	v_pk_fma_f32 v[190:191], v[160:161], v[86:87], v[90:91]
	v_pk_fma_f32 v[192:193], v[154:155], v[100:101], v[104:105]
	v_pk_fma_f32 v[194:195], v[156:157], v[102:103], v[106:107]
	v_fmac_f32_dpp v188, v158, v80 row_shr:1 row_mask:0xf bank_mask:0xf
	v_fmac_f32_dpp v189, v159, v81 row_shr:1 row_mask:0xf bank_mask:0xf
	v_fmac_f32_dpp v190, v160, v82 row_shr:1 row_mask:0xf bank_mask:0xf
	v_fmac_f32_dpp v191, v161, v83 row_shr:1 row_mask:0xf bank_mask:0xf
	v_fmac_f32_dpp v192, v154, v96 row_shr:1 row_mask:0xf bank_mask:0xf
	v_fmac_f32_dpp v193, v155, v97 row_shr:1 row_mask:0xf bank_mask:0xf
	v_fmac_f32_dpp v194, v156, v98 row_shr:1 row_mask:0xf bank_mask:0xf
	v_fmac_f32_dpp v195, v157, v99 row_shr:1 row_mask:0xf bank_mask:0xf
	v_fmac_f32_dpp v188, v158, v76 row_shr:2 row_mask:0xf bank_mask:0xf
	v_fmac_f32_dpp v189, v159, v77 row_shr:2 row_mask:0xf bank_mask:0xf
	v_fmac_f32_dpp v190, v160, v78 row_shr:2 row_mask:0xf bank_mask:0xf
	v_fmac_f32_dpp v191, v161, v79 row_shr:2 row_mask:0xf bank_mask:0xf
	v_fmac_f32_dpp v192, v154, v92 row_shr:2 row_mask:0xf bank_mask:0xf
	v_fmac_f32_dpp v193, v155, v93 row_shr:2 row_mask:0xf bank_mask:0xf
	v_fmac_f32_dpp v194, v156, v94 row_shr:2 row_mask:0xf bank_mask:0xf
	v_fmac_f32_dpp v195, v157, v95 row_shr:2 row_mask:0xf bank_mask:0xf
	v_pk_mul_f32 v[196:197], v[188:189], v[216:217] op_sel_hi:[1,0]
	v_pk_mul_f32 v[198:199], v[190:191], v[216:217] op_sel_hi:[1,0]
	v_exp_f32_e32 v196, v196
	v_exp_f32_e32 v197, v197
	v_exp_f32_e32 v198, v198
	v_exp_f32_e32 v199, v199
	v_pk_add_f32 v[196:197], v[196:197], v[214:215] op_sel_hi:[1,0]
	v_pk_add_f32 v[198:199], v[198:199], v[214:215] op_sel_hi:[1,0]
	v_rcp_f32_e32 v196, v196
	v_rcp_f32_e32 v197, v197
	v_rcp_f32_e32 v198, v198
	v_rcp_f32_e32 v199, v199
	v_pk_mul_f32 v[188:189], v[188:189], v[196:197]
	v_pk_mul_f32 v[190:191], v[190:191], v[198:199]
	v_pk_mul_f32 v[188:189], v[188:189], v[192:193]
	v_pk_mul_f32 v[190:191], v[190:191], v[194:195]
	v_cvt_pk_bf16_f32 v200, v188, v189
	v_cvt_pk_bf16_f32 v201, v190, v191
	v_pk_fma_f32 v[188:189], v[150:151], v[84:85], v[88:89]
	v_pk_fma_f32 v[190:191], v[152:153], v[86:87], v[90:91]
	v_pk_fma_f32 v[192:193], v[142:143], v[100:101], v[104:105]
	v_pk_fma_f32 v[194:195], v[144:145], v[102:103], v[106:107]
	v_cndmask_b32_e64 v158, v150, v158, s[10:11]
	v_cndmask_b32_e64 v159, v151, v159, s[10:11]
	v_cndmask_b32_e64 v160, v152, v160, s[10:11]
	v_cndmask_b32_e64 v161, v153, v161, s[10:11]
	v_cndmask_b32_e64 v154, v142, v154, s[10:11]
	v_cndmask_b32_e64 v155, v143, v155, s[10:11]
	v_cndmask_b32_e64 v156, v144, v156, s[10:11]
	v_cndmask_b32_e64 v157, v145, v157, s[10:11]
	v_fmac_f32_dpp v188, v158, v76 row_ror:2 row_mask:0xf bank_mask:0xf
	v_fmac_f32_dpp v189, v159, v77 row_ror:2 row_mask:0xf bank_mask:0xf
	v_fmac_f32_dpp v190, v160, v78 row_ror:2 row_mask:0xf bank_mask:0xf
	v_fmac_f32_dpp v191, v161, v79 row_ror:2 row_mask:0xf bank_mask:0xf
	v_fmac_f32_dpp v192, v154, v92 row_ror:2 row_mask:0xf bank_mask:0xf
	v_fmac_f32_dpp v193, v155, v93 row_ror:2 row_mask:0xf bank_mask:0xf
	v_fmac_f32_dpp v194, v156, v94 row_ror:2 row_mask:0xf bank_mask:0xf
	v_fmac_f32_dpp v195, v157, v95 row_ror:2 row_mask:0xf bank_mask:0xf
	v_cndmask_b32_e64 v158, v150, v158, s[8:9]
	v_cndmask_b32_e64 v159, v151, v159, s[8:9]
	v_cndmask_b32_e64 v160, v152, v160, s[8:9]
	v_cndmask_b32_e64 v161, v153, v161, s[8:9]
	v_cndmask_b32_e64 v154, v142, v154, s[8:9]
	v_cndmask_b32_e64 v155, v143, v155, s[8:9]
	v_cndmask_b32_e64 v156, v144, v156, s[8:9]
	v_cndmask_b32_e64 v157, v145, v157, s[8:9]
	v_fmac_f32_dpp v188, v158, v80 row_ror:1 row_mask:0xf bank_mask:0xf
	v_fmac_f32_dpp v189, v159, v81 row_ror:1 row_mask:0xf bank_mask:0xf
	v_fmac_f32_dpp v190, v160, v82 row_ror:1 row_mask:0xf bank_mask:0xf
	v_fmac_f32_dpp v191, v161, v83 row_ror:1 row_mask:0xf bank_mask:0xf
	v_fmac_f32_dpp v192, v154, v96 row_ror:1 row_mask:0xf bank_mask:0xf
	v_fmac_f32_dpp v193, v155, v97 row_ror:1 row_mask:0xf bank_mask:0xf
	v_fmac_f32_dpp v194, v156, v98 row_ror:1 row_mask:0xf bank_mask:0xf
	v_fmac_f32_dpp v195, v157, v99 row_ror:1 row_mask:0xf bank_mask:0xf
	v_pk_mul_f32 v[196:197], v[188:189], v[216:217] op_sel_hi:[1,0]
	v_pk_mul_f32 v[198:199], v[190:191], v[216:217] op_sel_hi:[1,0]
	v_exp_f32_e32 v196, v196
	v_exp_f32_e32 v197, v197
	v_exp_f32_e32 v198, v198
	v_exp_f32_e32 v199, v199
	v_pk_add_f32 v[196:197], v[196:197], v[214:215] op_sel_hi:[1,0]
	v_pk_add_f32 v[198:199], v[198:199], v[214:215] op_sel_hi:[1,0]
	v_rcp_f32_e32 v196, v196
	v_rcp_f32_e32 v197, v197
	v_rcp_f32_e32 v198, v198
	v_rcp_f32_e32 v199, v199
	v_pk_mul_f32 v[188:189], v[188:189], v[196:197]
	v_pk_mul_f32 v[190:191], v[190:191], v[198:199]
	v_pk_mul_f32 v[188:189], v[188:189], v[192:193]
	v_pk_mul_f32 v[190:191], v[190:191], v[194:195]
	v_cvt_pk_bf16_f32 v158, v188, v189
	v_cvt_pk_bf16_f32 v159, v190, v191
	global_load_dwordx4 v[154:157], v212, s[82:83] offset:16
	v_pk_fma_f32 v[188:189], v[146:147], v[84:85], v[88:89]
	v_pk_fma_f32 v[190:191], v[148:149], v[86:87], v[90:91]
	v_pk_fma_f32 v[192:193], v[134:135], v[100:101], v[104:105]
	v_pk_fma_f32 v[194:195], v[136:137], v[102:103], v[106:107]
	v_cndmask_b32_e64 v150, v146, v150, s[10:11]
	v_cndmask_b32_e64 v151, v147, v151, s[10:11]
	v_cndmask_b32_e64 v152, v148, v152, s[10:11]
	v_cndmask_b32_e64 v153, v149, v153, s[10:11]
	v_cndmask_b32_e64 v142, v134, v142, s[10:11]
	v_cndmask_b32_e64 v143, v135, v143, s[10:11]
	v_cndmask_b32_e64 v144, v136, v144, s[10:11]
	v_cndmask_b32_e64 v145, v137, v145, s[10:11]
	v_fmac_f32_dpp v188, v150, v76 row_ror:2 row_mask:0xf bank_mask:0xf
	v_fmac_f32_dpp v189, v151, v77 row_ror:2 row_mask:0xf bank_mask:0xf
	v_fmac_f32_dpp v190, v152, v78 row_ror:2 row_mask:0xf bank_mask:0xf
	v_fmac_f32_dpp v191, v153, v79 row_ror:2 row_mask:0xf bank_mask:0xf
	v_fmac_f32_dpp v192, v142, v92 row_ror:2 row_mask:0xf bank_mask:0xf
	v_fmac_f32_dpp v193, v143, v93 row_ror:2 row_mask:0xf bank_mask:0xf
	v_fmac_f32_dpp v194, v144, v94 row_ror:2 row_mask:0xf bank_mask:0xf
	v_fmac_f32_dpp v195, v145, v95 row_ror:2 row_mask:0xf bank_mask:0xf
	v_cndmask_b32_e64 v150, v146, v150, s[8:9]
	v_cndmask_b32_e64 v151, v147, v151, s[8:9]
	v_cndmask_b32_e64 v152, v148, v152, s[8:9]
	v_cndmask_b32_e64 v153, v149, v153, s[8:9]
	v_cndmask_b32_e64 v142, v134, v142, s[8:9]
	v_cndmask_b32_e64 v143, v135, v143, s[8:9]
	v_cndmask_b32_e64 v144, v136, v144, s[8:9]
	v_cndmask_b32_e64 v145, v137, v145, s[8:9]
	v_fmac_f32_dpp v188, v150, v80 row_ror:1 row_mask:0xf bank_mask:0xf
	v_fmac_f32_dpp v189, v151, v81 row_ror:1 row_mask:0xf bank_mask:0xf
	v_fmac_f32_dpp v190, v152, v82 row_ror:1 row_mask:0xf bank_mask:0xf
	v_fmac_f32_dpp v191, v153, v83 row_ror:1 row_mask:0xf bank_mask:0xf
	v_fmac_f32_dpp v192, v142, v96 row_ror:1 row_mask:0xf bank_mask:0xf
	v_fmac_f32_dpp v193, v143, v97 row_ror:1 row_mask:0xf bank_mask:0xf
	v_fmac_f32_dpp v194, v144, v98 row_ror:1 row_mask:0xf bank_mask:0xf
	v_fmac_f32_dpp v195, v145, v99 row_ror:1 row_mask:0xf bank_mask:0xf
	v_pk_mul_f32 v[196:197], v[188:189], v[216:217] op_sel_hi:[1,0]
	v_pk_mul_f32 v[198:199], v[190:191], v[216:217] op_sel_hi:[1,0]
	v_exp_f32_e32 v196, v196
	v_exp_f32_e32 v197, v197
	v_exp_f32_e32 v198, v198
	v_exp_f32_e32 v199, v199
	v_pk_add_f32 v[196:197], v[196:197], v[214:215] op_sel_hi:[1,0]
	v_pk_add_f32 v[198:199], v[198:199], v[214:215] op_sel_hi:[1,0]
	v_rcp_f32_e32 v196, v196
	v_rcp_f32_e32 v197, v197
	v_rcp_f32_e32 v198, v198
	v_rcp_f32_e32 v199, v199
	v_pk_mul_f32 v[188:189], v[188:189], v[196:197]
	v_pk_mul_f32 v[190:191], v[190:191], v[198:199]
	v_pk_mul_f32 v[188:189], v[188:189], v[192:193]
	v_pk_mul_f32 v[190:191], v[190:191], v[194:195]
	v_cvt_pk_bf16_f32 v150, v188, v189
	v_cvt_pk_bf16_f32 v151, v190, v191
	v_add_u32_e32 v213, 0xb000, v212
	global_load_dwordx4 v[142:145], v213, s[82:83] offset:16
	v_pk_fma_f32 v[188:189], v[138:139], v[84:85], v[88:89]
	v_pk_fma_f32 v[190:191], v[140:141], v[86:87], v[90:91]
	v_pk_fma_f32 v[192:193], v[130:131], v[100:101], v[104:105]
	v_pk_fma_f32 v[194:195], v[132:133], v[102:103], v[106:107]
	v_cndmask_b32_e64 v146, v138, v146, s[10:11]
	v_cndmask_b32_e64 v147, v139, v147, s[10:11]
	v_cndmask_b32_e64 v148, v140, v148, s[10:11]
	v_cndmask_b32_e64 v149, v141, v149, s[10:11]
	v_cndmask_b32_e64 v134, v130, v134, s[10:11]
	v_cndmask_b32_e64 v135, v131, v135, s[10:11]
	v_cndmask_b32_e64 v136, v132, v136, s[10:11]
	v_cndmask_b32_e64 v137, v133, v137, s[10:11]
	v_fmac_f32_dpp v188, v146, v76 row_ror:2 row_mask:0xf bank_mask:0xf
	v_fmac_f32_dpp v189, v147, v77 row_ror:2 row_mask:0xf bank_mask:0xf
	v_fmac_f32_dpp v190, v148, v78 row_ror:2 row_mask:0xf bank_mask:0xf
	v_fmac_f32_dpp v191, v149, v79 row_ror:2 row_mask:0xf bank_mask:0xf
	v_fmac_f32_dpp v192, v134, v92 row_ror:2 row_mask:0xf bank_mask:0xf
	v_fmac_f32_dpp v193, v135, v93 row_ror:2 row_mask:0xf bank_mask:0xf
	v_fmac_f32_dpp v194, v136, v94 row_ror:2 row_mask:0xf bank_mask:0xf
	v_fmac_f32_dpp v195, v137, v95 row_ror:2 row_mask:0xf bank_mask:0xf
	v_cndmask_b32_e64 v146, v138, v146, s[8:9]
	v_cndmask_b32_e64 v147, v139, v147, s[8:9]
	v_cndmask_b32_e64 v148, v140, v148, s[8:9]
	v_cndmask_b32_e64 v149, v141, v149, s[8:9]
	v_cndmask_b32_e64 v134, v130, v134, s[8:9]
	v_cndmask_b32_e64 v135, v131, v135, s[8:9]
	v_cndmask_b32_e64 v136, v132, v136, s[8:9]
	v_cndmask_b32_e64 v137, v133, v137, s[8:9]
	v_fmac_f32_dpp v188, v146, v80 row_ror:1 row_mask:0xf bank_mask:0xf
	v_fmac_f32_dpp v189, v147, v81 row_ror:1 row_mask:0xf bank_mask:0xf
	v_fmac_f32_dpp v190, v148, v82 row_ror:1 row_mask:0xf bank_mask:0xf
	v_fmac_f32_dpp v191, v149, v83 row_ror:1 row_mask:0xf bank_mask:0xf
	v_fmac_f32_dpp v192, v134, v96 row_ror:1 row_mask:0xf bank_mask:0xf
	v_fmac_f32_dpp v193, v135, v97 row_ror:1 row_mask:0xf bank_mask:0xf
	v_fmac_f32_dpp v194, v136, v98 row_ror:1 row_mask:0xf bank_mask:0xf
	v_fmac_f32_dpp v195, v137, v99 row_ror:1 row_mask:0xf bank_mask:0xf
	v_pk_mul_f32 v[196:197], v[188:189], v[216:217] op_sel_hi:[1,0]
	v_pk_mul_f32 v[198:199], v[190:191], v[216:217] op_sel_hi:[1,0]
	v_exp_f32_e32 v196, v196
	v_exp_f32_e32 v197, v197
	v_exp_f32_e32 v198, v198
	v_exp_f32_e32 v199, v199
	v_pk_add_f32 v[196:197], v[196:197], v[214:215] op_sel_hi:[1,0]
	v_pk_add_f32 v[198:199], v[198:199], v[214:215] op_sel_hi:[1,0]
	v_rcp_f32_e32 v196, v196
	v_rcp_f32_e32 v197, v197
	v_rcp_f32_e32 v198, v198
	v_rcp_f32_e32 v199, v199
	v_pk_mul_f32 v[188:189], v[188:189], v[196:197]
	v_pk_mul_f32 v[190:191], v[190:191], v[198:199]
	v_pk_mul_f32 v[188:189], v[188:189], v[192:193]
	v_pk_mul_f32 v[190:191], v[190:191], v[194:195]
	v_cvt_pk_bf16_f32 v146, v188, v189
	v_cvt_pk_bf16_f32 v147, v190, v191
	v_add_u32_e32 v213, 0x16000, v212
	global_load_dwordx4 v[134:137], v213, s[82:83] offset:16
	v_pk_fma_f32 v[188:189], v[126:127], v[84:85], v[88:89]
	v_pk_fma_f32 v[190:191], v[128:129], v[86:87], v[90:91]
	v_pk_fma_f32 v[192:193], v[118:119], v[100:101], v[104:105]
	v_pk_fma_f32 v[194:195], v[120:121], v[102:103], v[106:107]
	v_cndmask_b32_e64 v138, v126, v138, s[10:11]
	v_cndmask_b32_e64 v139, v127, v139, s[10:11]
	v_cndmask_b32_e64 v140, v128, v140, s[10:11]
	v_cndmask_b32_e64 v141, v129, v141, s[10:11]
	v_cndmask_b32_e64 v130, v118, v130, s[10:11]
	v_cndmask_b32_e64 v131, v119, v131, s[10:11]
	v_cndmask_b32_e64 v132, v120, v132, s[10:11]
	v_cndmask_b32_e64 v133, v121, v133, s[10:11]
	v_fmac_f32_dpp v188, v138, v76 row_ror:2 row_mask:0xf bank_mask:0xf
	v_fmac_f32_dpp v189, v139, v77 row_ror:2 row_mask:0xf bank_mask:0xf
	v_fmac_f32_dpp v190, v140, v78 row_ror:2 row_mask:0xf bank_mask:0xf
	v_fmac_f32_dpp v191, v141, v79 row_ror:2 row_mask:0xf bank_mask:0xf
	v_fmac_f32_dpp v192, v130, v92 row_ror:2 row_mask:0xf bank_mask:0xf
	v_fmac_f32_dpp v193, v131, v93 row_ror:2 row_mask:0xf bank_mask:0xf
	v_fmac_f32_dpp v194, v132, v94 row_ror:2 row_mask:0xf bank_mask:0xf
	v_fmac_f32_dpp v195, v133, v95 row_ror:2 row_mask:0xf bank_mask:0xf
	v_cndmask_b32_e64 v138, v126, v138, s[8:9]
	v_cndmask_b32_e64 v139, v127, v139, s[8:9]
	v_cndmask_b32_e64 v140, v128, v140, s[8:9]
	v_cndmask_b32_e64 v141, v129, v141, s[8:9]
	v_cndmask_b32_e64 v130, v118, v130, s[8:9]
	v_cndmask_b32_e64 v131, v119, v131, s[8:9]
	v_cndmask_b32_e64 v132, v120, v132, s[8:9]
	v_cndmask_b32_e64 v133, v121, v133, s[8:9]
	v_fmac_f32_dpp v188, v138, v80 row_ror:1 row_mask:0xf bank_mask:0xf
	v_fmac_f32_dpp v189, v139, v81 row_ror:1 row_mask:0xf bank_mask:0xf
	v_fmac_f32_dpp v190, v140, v82 row_ror:1 row_mask:0xf bank_mask:0xf
	v_fmac_f32_dpp v191, v141, v83 row_ror:1 row_mask:0xf bank_mask:0xf
	v_fmac_f32_dpp v192, v130, v96 row_ror:1 row_mask:0xf bank_mask:0xf
	v_fmac_f32_dpp v193, v131, v97 row_ror:1 row_mask:0xf bank_mask:0xf
	v_fmac_f32_dpp v194, v132, v98 row_ror:1 row_mask:0xf bank_mask:0xf
	v_fmac_f32_dpp v195, v133, v99 row_ror:1 row_mask:0xf bank_mask:0xf
	v_pk_mul_f32 v[196:197], v[188:189], v[216:217] op_sel_hi:[1,0]
	v_pk_mul_f32 v[198:199], v[190:191], v[216:217] op_sel_hi:[1,0]
	v_exp_f32_e32 v196, v196
	v_exp_f32_e32 v197, v197
	v_exp_f32_e32 v198, v198
	v_exp_f32_e32 v199, v199
	v_pk_add_f32 v[196:197], v[196:197], v[214:215] op_sel_hi:[1,0]
	v_pk_add_f32 v[198:199], v[198:199], v[214:215] op_sel_hi:[1,0]
	v_rcp_f32_e32 v196, v196
	v_rcp_f32_e32 v197, v197
	v_rcp_f32_e32 v198, v198
	v_rcp_f32_e32 v199, v199
	v_pk_mul_f32 v[188:189], v[188:189], v[196:197]
	v_pk_mul_f32 v[190:191], v[190:191], v[198:199]
	v_pk_mul_f32 v[188:189], v[188:189], v[192:193]
	v_pk_mul_f32 v[190:191], v[190:191], v[194:195]
	v_cvt_pk_bf16_f32 v138, v188, v189
	v_cvt_pk_bf16_f32 v139, v190, v191
	global_load_dwordx4 v[130:133], v212, s[84:85] offset:16
	v_pk_fma_f32 v[188:189], v[122:123], v[84:85], v[88:89]
	v_pk_fma_f32 v[190:191], v[124:125], v[86:87], v[90:91]
	v_pk_fma_f32 v[192:193], v[110:111], v[100:101], v[104:105]
	v_pk_fma_f32 v[194:195], v[112:113], v[102:103], v[106:107]
	v_cndmask_b32_e64 v126, v122, v126, s[10:11]
	v_cndmask_b32_e64 v127, v123, v127, s[10:11]
	v_cndmask_b32_e64 v128, v124, v128, s[10:11]
	v_cndmask_b32_e64 v129, v125, v129, s[10:11]
	v_cndmask_b32_e64 v118, v110, v118, s[10:11]
	v_cndmask_b32_e64 v119, v111, v119, s[10:11]
	v_cndmask_b32_e64 v120, v112, v120, s[10:11]
	v_cndmask_b32_e64 v121, v113, v121, s[10:11]
	v_fmac_f32_dpp v188, v126, v76 row_ror:2 row_mask:0xf bank_mask:0xf
	v_fmac_f32_dpp v189, v127, v77 row_ror:2 row_mask:0xf bank_mask:0xf
	v_fmac_f32_dpp v190, v128, v78 row_ror:2 row_mask:0xf bank_mask:0xf
	v_fmac_f32_dpp v191, v129, v79 row_ror:2 row_mask:0xf bank_mask:0xf
	v_fmac_f32_dpp v192, v118, v92 row_ror:2 row_mask:0xf bank_mask:0xf
	v_fmac_f32_dpp v193, v119, v93 row_ror:2 row_mask:0xf bank_mask:0xf
	v_fmac_f32_dpp v194, v120, v94 row_ror:2 row_mask:0xf bank_mask:0xf
	v_fmac_f32_dpp v195, v121, v95 row_ror:2 row_mask:0xf bank_mask:0xf
	v_cndmask_b32_e64 v126, v122, v126, s[8:9]
	v_cndmask_b32_e64 v127, v123, v127, s[8:9]
	v_cndmask_b32_e64 v128, v124, v128, s[8:9]
	v_cndmask_b32_e64 v129, v125, v129, s[8:9]
	v_cndmask_b32_e64 v118, v110, v118, s[8:9]
	v_cndmask_b32_e64 v119, v111, v119, s[8:9]
	v_cndmask_b32_e64 v120, v112, v120, s[8:9]
	v_cndmask_b32_e64 v121, v113, v121, s[8:9]
	v_fmac_f32_dpp v188, v126, v80 row_ror:1 row_mask:0xf bank_mask:0xf
	v_fmac_f32_dpp v189, v127, v81 row_ror:1 row_mask:0xf bank_mask:0xf
	v_fmac_f32_dpp v190, v128, v82 row_ror:1 row_mask:0xf bank_mask:0xf
	v_fmac_f32_dpp v191, v129, v83 row_ror:1 row_mask:0xf bank_mask:0xf
	v_fmac_f32_dpp v192, v118, v96 row_ror:1 row_mask:0xf bank_mask:0xf
	v_fmac_f32_dpp v193, v119, v97 row_ror:1 row_mask:0xf bank_mask:0xf
	v_fmac_f32_dpp v194, v120, v98 row_ror:1 row_mask:0xf bank_mask:0xf
	v_fmac_f32_dpp v195, v121, v99 row_ror:1 row_mask:0xf bank_mask:0xf
	v_pk_mul_f32 v[196:197], v[188:189], v[216:217] op_sel_hi:[1,0]
	v_pk_mul_f32 v[198:199], v[190:191], v[216:217] op_sel_hi:[1,0]
	v_exp_f32_e32 v196, v196
	v_exp_f32_e32 v197, v197
	v_exp_f32_e32 v198, v198
	v_exp_f32_e32 v199, v199
	v_pk_add_f32 v[196:197], v[196:197], v[214:215] op_sel_hi:[1,0]
	v_pk_add_f32 v[198:199], v[198:199], v[214:215] op_sel_hi:[1,0]
	v_rcp_f32_e32 v196, v196
	v_rcp_f32_e32 v197, v197
	v_rcp_f32_e32 v198, v198
	v_rcp_f32_e32 v199, v199
	v_pk_mul_f32 v[188:189], v[188:189], v[196:197]
	v_pk_mul_f32 v[190:191], v[190:191], v[198:199]
	v_pk_mul_f32 v[188:189], v[188:189], v[192:193]
	v_pk_mul_f32 v[190:191], v[190:191], v[194:195]
	v_cvt_pk_bf16_f32 v126, v188, v189
	v_cvt_pk_bf16_f32 v127, v190, v191
	v_add_u32_e32 v213, 0x5800, v212
	global_load_dwordx4 v[118:121], v213, s[82:83] offset:16
	v_pk_fma_f32 v[188:189], v[114:115], v[84:85], v[88:89]
	v_pk_fma_f32 v[190:191], v[116:117], v[86:87], v[90:91]
	v_pk_fma_f32 v[192:193], v[68:69], v[100:101], v[104:105]
	v_pk_fma_f32 v[194:195], v[70:71], v[102:103], v[106:107]
	v_cndmask_b32_e64 v122, v114, v122, s[10:11]
	v_cndmask_b32_e64 v123, v115, v123, s[10:11]
	v_cndmask_b32_e64 v124, v116, v124, s[10:11]
	v_cndmask_b32_e64 v125, v117, v125, s[10:11]
	v_cndmask_b32_e64 v110, v68, v110, s[10:11]
	v_cndmask_b32_e64 v111, v69, v111, s[10:11]
	v_cndmask_b32_e64 v112, v70, v112, s[10:11]
	v_cndmask_b32_e64 v113, v71, v113, s[10:11]
	v_fmac_f32_dpp v188, v122, v76 row_ror:2 row_mask:0xf bank_mask:0xf
	v_fmac_f32_dpp v189, v123, v77 row_ror:2 row_mask:0xf bank_mask:0xf
	v_fmac_f32_dpp v190, v124, v78 row_ror:2 row_mask:0xf bank_mask:0xf
	v_fmac_f32_dpp v191, v125, v79 row_ror:2 row_mask:0xf bank_mask:0xf
	v_fmac_f32_dpp v192, v110, v92 row_ror:2 row_mask:0xf bank_mask:0xf
	v_fmac_f32_dpp v193, v111, v93 row_ror:2 row_mask:0xf bank_mask:0xf
	v_fmac_f32_dpp v194, v112, v94 row_ror:2 row_mask:0xf bank_mask:0xf
	v_fmac_f32_dpp v195, v113, v95 row_ror:2 row_mask:0xf bank_mask:0xf
	v_cndmask_b32_e64 v122, v114, v122, s[8:9]
	v_cndmask_b32_e64 v123, v115, v123, s[8:9]
	v_cndmask_b32_e64 v124, v116, v124, s[8:9]
	v_cndmask_b32_e64 v125, v117, v125, s[8:9]
	v_cndmask_b32_e64 v110, v68, v110, s[8:9]
	v_cndmask_b32_e64 v111, v69, v111, s[8:9]
	v_cndmask_b32_e64 v112, v70, v112, s[8:9]
	v_cndmask_b32_e64 v113, v71, v113, s[8:9]
	v_fmac_f32_dpp v188, v122, v80 row_ror:1 row_mask:0xf bank_mask:0xf
	v_fmac_f32_dpp v189, v123, v81 row_ror:1 row_mask:0xf bank_mask:0xf
	v_fmac_f32_dpp v190, v124, v82 row_ror:1 row_mask:0xf bank_mask:0xf
	v_fmac_f32_dpp v191, v125, v83 row_ror:1 row_mask:0xf bank_mask:0xf
	v_fmac_f32_dpp v192, v110, v96 row_ror:1 row_mask:0xf bank_mask:0xf
	v_fmac_f32_dpp v193, v111, v97 row_ror:1 row_mask:0xf bank_mask:0xf
	v_fmac_f32_dpp v194, v112, v98 row_ror:1 row_mask:0xf bank_mask:0xf
	v_fmac_f32_dpp v195, v113, v99 row_ror:1 row_mask:0xf bank_mask:0xf
	v_pk_mul_f32 v[196:197], v[188:189], v[216:217] op_sel_hi:[1,0]
	v_pk_mul_f32 v[198:199], v[190:191], v[216:217] op_sel_hi:[1,0]
	v_exp_f32_e32 v196, v196
	v_exp_f32_e32 v197, v197
	v_exp_f32_e32 v198, v198
	v_exp_f32_e32 v199, v199
	v_pk_add_f32 v[196:197], v[196:197], v[214:215] op_sel_hi:[1,0]
	v_pk_add_f32 v[198:199], v[198:199], v[214:215] op_sel_hi:[1,0]
	v_rcp_f32_e32 v196, v196
	v_rcp_f32_e32 v197, v197
	v_rcp_f32_e32 v198, v198
	v_rcp_f32_e32 v199, v199
	v_pk_mul_f32 v[188:189], v[188:189], v[196:197]
	v_pk_mul_f32 v[190:191], v[190:191], v[198:199]
	v_pk_mul_f32 v[188:189], v[188:189], v[192:193]
	v_pk_mul_f32 v[190:191], v[190:191], v[194:195]
	v_cvt_pk_bf16_f32 v122, v188, v189
	v_cvt_pk_bf16_f32 v123, v190, v191
	v_add_u32_e32 v213, 0x10800, v212
	global_load_dwordx4 v[110:113], v213, s[82:83] offset:16
	v_pk_fma_f32 v[188:189], v[72:73], v[84:85], v[88:89]
	v_pk_fma_f32 v[190:191], v[74:75], v[86:87], v[90:91]
	v_pk_fma_f32 v[192:193], v[64:65], v[100:101], v[104:105]
	v_pk_fma_f32 v[194:195], v[66:67], v[102:103], v[106:107]
	v_cndmask_b32_e64 v114, v72, v114, s[10:11]
	v_cndmask_b32_e64 v115, v73, v115, s[10:11]
	v_cndmask_b32_e64 v116, v74, v116, s[10:11]
	v_cndmask_b32_e64 v117, v75, v117, s[10:11]
	v_cndmask_b32_e64 v68, v64, v68, s[10:11]
	v_cndmask_b32_e64 v69, v65, v69, s[10:11]
	v_cndmask_b32_e64 v70, v66, v70, s[10:11]
	v_cndmask_b32_e64 v71, v67, v71, s[10:11]
	v_fmac_f32_dpp v188, v114, v76 row_ror:2 row_mask:0xf bank_mask:0xf
	v_fmac_f32_dpp v189, v115, v77 row_ror:2 row_mask:0xf bank_mask:0xf
	v_fmac_f32_dpp v190, v116, v78 row_ror:2 row_mask:0xf bank_mask:0xf
	v_fmac_f32_dpp v191, v117, v79 row_ror:2 row_mask:0xf bank_mask:0xf
	v_fmac_f32_dpp v192, v68, v92 row_ror:2 row_mask:0xf bank_mask:0xf
	v_fmac_f32_dpp v193, v69, v93 row_ror:2 row_mask:0xf bank_mask:0xf
	v_fmac_f32_dpp v194, v70, v94 row_ror:2 row_mask:0xf bank_mask:0xf
	v_fmac_f32_dpp v195, v71, v95 row_ror:2 row_mask:0xf bank_mask:0xf
	v_cndmask_b32_e64 v114, v72, v114, s[8:9]
	v_cndmask_b32_e64 v115, v73, v115, s[8:9]
	v_cndmask_b32_e64 v116, v74, v116, s[8:9]
	v_cndmask_b32_e64 v117, v75, v117, s[8:9]
	v_cndmask_b32_e64 v68, v64, v68, s[8:9]
	v_cndmask_b32_e64 v69, v65, v69, s[8:9]
	v_cndmask_b32_e64 v70, v66, v70, s[8:9]
	v_cndmask_b32_e64 v71, v67, v71, s[8:9]
	v_fmac_f32_dpp v188, v114, v80 row_ror:1 row_mask:0xf bank_mask:0xf
	v_fmac_f32_dpp v189, v115, v81 row_ror:1 row_mask:0xf bank_mask:0xf
	v_fmac_f32_dpp v190, v116, v82 row_ror:1 row_mask:0xf bank_mask:0xf
	v_fmac_f32_dpp v191, v117, v83 row_ror:1 row_mask:0xf bank_mask:0xf
	v_fmac_f32_dpp v192, v68, v96 row_ror:1 row_mask:0xf bank_mask:0xf
	v_fmac_f32_dpp v193, v69, v97 row_ror:1 row_mask:0xf bank_mask:0xf
	v_fmac_f32_dpp v194, v70, v98 row_ror:1 row_mask:0xf bank_mask:0xf
	v_fmac_f32_dpp v195, v71, v99 row_ror:1 row_mask:0xf bank_mask:0xf
	v_pk_mul_f32 v[196:197], v[188:189], v[216:217] op_sel_hi:[1,0]
	v_pk_mul_f32 v[198:199], v[190:191], v[216:217] op_sel_hi:[1,0]
	v_exp_f32_e32 v196, v196
	v_exp_f32_e32 v197, v197
	v_exp_f32_e32 v198, v198
	v_exp_f32_e32 v199, v199
	v_pk_add_f32 v[196:197], v[196:197], v[214:215] op_sel_hi:[1,0]
	v_pk_add_f32 v[198:199], v[198:199], v[214:215] op_sel_hi:[1,0]
	v_rcp_f32_e32 v196, v196
	v_rcp_f32_e32 v197, v197
	v_rcp_f32_e32 v198, v198
	v_rcp_f32_e32 v199, v199
	v_pk_mul_f32 v[188:189], v[188:189], v[196:197]
	v_pk_mul_f32 v[190:191], v[190:191], v[198:199]
	v_pk_mul_f32 v[188:189], v[188:189], v[192:193]
	v_pk_mul_f32 v[190:191], v[190:191], v[194:195]
	v_cvt_pk_bf16_f32 v114, v188, v189
	v_cvt_pk_bf16_f32 v115, v190, v191
	s_waitcnt vmcnt(0)
	v_pk_fma_f32 v[188:189], v[60:61], v[134:135], v[130:131]
	v_pk_fma_f32 v[190:191], v[62:63], v[136:137], v[132:133]
	v_pk_fma_f32 v[192:193], v[56:57], v[204:205], v[208:209]
	v_pk_fma_f32 v[194:195], v[58:59], v[206:207], v[210:211]
	v_fmac_f32_dpp v188, v60, v142 row_shr:1 row_mask:0xf bank_mask:0xf
	v_fmac_f32_dpp v189, v61, v143 row_shr:1 row_mask:0xf bank_mask:0xf
	v_fmac_f32_dpp v190, v62, v144 row_shr:1 row_mask:0xf bank_mask:0xf
	v_fmac_f32_dpp v191, v63, v145 row_shr:1 row_mask:0xf bank_mask:0xf
	v_fmac_f32_dpp v192, v56, v110 row_shr:1 row_mask:0xf bank_mask:0xf
	v_fmac_f32_dpp v193, v57, v111 row_shr:1 row_mask:0xf bank_mask:0xf
	v_fmac_f32_dpp v194, v58, v112 row_shr:1 row_mask:0xf bank_mask:0xf
	v_fmac_f32_dpp v195, v59, v113 row_shr:1 row_mask:0xf bank_mask:0xf
	v_fmac_f32_dpp v188, v60, v154 row_shr:2 row_mask:0xf bank_mask:0xf
	v_fmac_f32_dpp v189, v61, v155 row_shr:2 row_mask:0xf bank_mask:0xf
	v_fmac_f32_dpp v190, v62, v156 row_shr:2 row_mask:0xf bank_mask:0xf
	v_fmac_f32_dpp v191, v63, v157 row_shr:2 row_mask:0xf bank_mask:0xf
	v_fmac_f32_dpp v192, v56, v118 row_shr:2 row_mask:0xf bank_mask:0xf
	v_fmac_f32_dpp v193, v57, v119 row_shr:2 row_mask:0xf bank_mask:0xf
	v_fmac_f32_dpp v194, v58, v120 row_shr:2 row_mask:0xf bank_mask:0xf
	v_fmac_f32_dpp v195, v59, v121 row_shr:2 row_mask:0xf bank_mask:0xf
	v_pk_mul_f32 v[196:197], v[188:189], v[216:217] op_sel_hi:[1,0]
	v_pk_mul_f32 v[198:199], v[190:191], v[216:217] op_sel_hi:[1,0]
	v_exp_f32_e32 v196, v196
	v_exp_f32_e32 v197, v197
	v_exp_f32_e32 v198, v198
	v_exp_f32_e32 v199, v199
	v_pk_add_f32 v[196:197], v[196:197], v[214:215] op_sel_hi:[1,0]
	v_pk_add_f32 v[198:199], v[198:199], v[214:215] op_sel_hi:[1,0]
	v_rcp_f32_e32 v196, v196
	v_rcp_f32_e32 v197, v197
	v_rcp_f32_e32 v198, v198
	v_rcp_f32_e32 v199, v199
	v_pk_mul_f32 v[188:189], v[188:189], v[196:197]
	v_pk_mul_f32 v[190:191], v[190:191], v[198:199]
	v_pk_mul_f32 v[188:189], v[188:189], v[192:193]
	v_pk_mul_f32 v[190:191], v[190:191], v[194:195]
	v_cvt_pk_bf16_f32 v202, v188, v189
	v_cvt_pk_bf16_f32 v203, v190, v191
	s_mov_b64 exec, vcc
	global_store_dwordx4 v215, v[200:203], s[96:97] nt
	s_mov_b64 exec, -1
	v_pk_fma_f32 v[188:189], v[52:53], v[134:135], v[130:131]
	v_pk_fma_f32 v[190:191], v[54:55], v[136:137], v[132:133]
	v_pk_fma_f32 v[192:193], v[44:45], v[204:205], v[208:209]
	v_pk_fma_f32 v[194:195], v[46:47], v[206:207], v[210:211]
	v_cndmask_b32_e64 v60, v52, v60, s[10:11]
	v_cndmask_b32_e64 v61, v53, v61, s[10:11]
	v_cndmask_b32_e64 v62, v54, v62, s[10:11]
	v_cndmask_b32_e64 v63, v55, v63, s[10:11]
	v_cndmask_b32_e64 v56, v44, v56, s[10:11]
	v_cndmask_b32_e64 v57, v45, v57, s[10:11]
	v_cndmask_b32_e64 v58, v46, v58, s[10:11]
	v_cndmask_b32_e64 v59, v47, v59, s[10:11]
	v_fmac_f32_dpp v188, v60, v154 row_ror:2 row_mask:0xf bank_mask:0xf
	v_fmac_f32_dpp v189, v61, v155 row_ror:2 row_mask:0xf bank_mask:0xf
	v_fmac_f32_dpp v190, v62, v156 row_ror:2 row_mask:0xf bank_mask:0xf
	v_fmac_f32_dpp v191, v63, v157 row_ror:2 row_mask:0xf bank_mask:0xf
	v_fmac_f32_dpp v192, v56, v118 row_ror:2 row_mask:0xf bank_mask:0xf
	v_fmac_f32_dpp v193, v57, v119 row_ror:2 row_mask:0xf bank_mask:0xf
	v_fmac_f32_dpp v194, v58, v120 row_ror:2 row_mask:0xf bank_mask:0xf
	v_fmac_f32_dpp v195, v59, v121 row_ror:2 row_mask:0xf bank_mask:0xf
	v_cndmask_b32_e64 v60, v52, v60, s[8:9]
	v_cndmask_b32_e64 v61, v53, v61, s[8:9]
	v_cndmask_b32_e64 v62, v54, v62, s[8:9]
	v_cndmask_b32_e64 v63, v55, v63, s[8:9]
	v_cndmask_b32_e64 v56, v44, v56, s[8:9]
	v_cndmask_b32_e64 v57, v45, v57, s[8:9]
	v_cndmask_b32_e64 v58, v46, v58, s[8:9]
	v_cndmask_b32_e64 v59, v47, v59, s[8:9]
	v_fmac_f32_dpp v188, v60, v142 row_ror:1 row_mask:0xf bank_mask:0xf
	v_fmac_f32_dpp v189, v61, v143 row_ror:1 row_mask:0xf bank_mask:0xf
	v_fmac_f32_dpp v190, v62, v144 row_ror:1 row_mask:0xf bank_mask:0xf
	v_fmac_f32_dpp v191, v63, v145 row_ror:1 row_mask:0xf bank_mask:0xf
	v_fmac_f32_dpp v192, v56, v110 row_ror:1 row_mask:0xf bank_mask:0xf
	v_fmac_f32_dpp v193, v57, v111 row_ror:1 row_mask:0xf bank_mask:0xf
	v_fmac_f32_dpp v194, v58, v112 row_ror:1 row_mask:0xf bank_mask:0xf
	v_fmac_f32_dpp v195, v59, v113 row_ror:1 row_mask:0xf bank_mask:0xf
	v_pk_mul_f32 v[196:197], v[188:189], v[216:217] op_sel_hi:[1,0]
	v_pk_mul_f32 v[198:199], v[190:191], v[216:217] op_sel_hi:[1,0]
	v_exp_f32_e32 v196, v196
	v_exp_f32_e32 v197, v197
	v_exp_f32_e32 v198, v198
	v_exp_f32_e32 v199, v199
	v_pk_add_f32 v[196:197], v[196:197], v[214:215] op_sel_hi:[1,0]
	v_pk_add_f32 v[198:199], v[198:199], v[214:215] op_sel_hi:[1,0]
	v_rcp_f32_e32 v196, v196
	v_rcp_f32_e32 v197, v197
	v_rcp_f32_e32 v198, v198
	v_rcp_f32_e32 v199, v199
	v_pk_mul_f32 v[188:189], v[188:189], v[196:197]
	v_pk_mul_f32 v[190:191], v[190:191], v[198:199]
	v_pk_mul_f32 v[188:189], v[188:189], v[192:193]
	v_pk_mul_f32 v[190:191], v[190:191], v[194:195]
	v_cvt_pk_bf16_f32 v160, v188, v189
	v_cvt_pk_bf16_f32 v161, v190, v191
	v_add_u32_e32 v213, 0x2c000, v215
	global_store_dwordx4 v213, v[158:161], s[96:97] nt
	v_pk_fma_f32 v[188:189], v[48:49], v[134:135], v[130:131]
	v_pk_fma_f32 v[190:191], v[50:51], v[136:137], v[132:133]
	v_pk_fma_f32 v[192:193], v[36:37], v[204:205], v[208:209]
	v_pk_fma_f32 v[194:195], v[38:39], v[206:207], v[210:211]
	v_cndmask_b32_e64 v52, v48, v52, s[10:11]
	v_cndmask_b32_e64 v53, v49, v53, s[10:11]
	v_cndmask_b32_e64 v54, v50, v54, s[10:11]
	v_cndmask_b32_e64 v55, v51, v55, s[10:11]
	v_cndmask_b32_e64 v44, v36, v44, s[10:11]
	v_cndmask_b32_e64 v45, v37, v45, s[10:11]
	v_cndmask_b32_e64 v46, v38, v46, s[10:11]
	v_cndmask_b32_e64 v47, v39, v47, s[10:11]
	v_fmac_f32_dpp v188, v52, v154 row_ror:2 row_mask:0xf bank_mask:0xf
	v_fmac_f32_dpp v189, v53, v155 row_ror:2 row_mask:0xf bank_mask:0xf
	v_fmac_f32_dpp v190, v54, v156 row_ror:2 row_mask:0xf bank_mask:0xf
	v_fmac_f32_dpp v191, v55, v157 row_ror:2 row_mask:0xf bank_mask:0xf
	v_fmac_f32_dpp v192, v44, v118 row_ror:2 row_mask:0xf bank_mask:0xf
	v_fmac_f32_dpp v193, v45, v119 row_ror:2 row_mask:0xf bank_mask:0xf
	v_fmac_f32_dpp v194, v46, v120 row_ror:2 row_mask:0xf bank_mask:0xf
	v_fmac_f32_dpp v195, v47, v121 row_ror:2 row_mask:0xf bank_mask:0xf
	v_cndmask_b32_e64 v52, v48, v52, s[8:9]
	v_cndmask_b32_e64 v53, v49, v53, s[8:9]
	v_cndmask_b32_e64 v54, v50, v54, s[8:9]
	v_cndmask_b32_e64 v55, v51, v55, s[8:9]
	v_cndmask_b32_e64 v44, v36, v44, s[8:9]
	v_cndmask_b32_e64 v45, v37, v45, s[8:9]
	v_cndmask_b32_e64 v46, v38, v46, s[8:9]
	v_cndmask_b32_e64 v47, v39, v47, s[8:9]
	v_fmac_f32_dpp v188, v52, v142 row_ror:1 row_mask:0xf bank_mask:0xf
	v_fmac_f32_dpp v189, v53, v143 row_ror:1 row_mask:0xf bank_mask:0xf
	v_fmac_f32_dpp v190, v54, v144 row_ror:1 row_mask:0xf bank_mask:0xf
	v_fmac_f32_dpp v191, v55, v145 row_ror:1 row_mask:0xf bank_mask:0xf
	v_fmac_f32_dpp v192, v44, v110 row_ror:1 row_mask:0xf bank_mask:0xf
	v_fmac_f32_dpp v193, v45, v111 row_ror:1 row_mask:0xf bank_mask:0xf
	v_fmac_f32_dpp v194, v46, v112 row_ror:1 row_mask:0xf bank_mask:0xf
	v_fmac_f32_dpp v195, v47, v113 row_ror:1 row_mask:0xf bank_mask:0xf
	v_pk_mul_f32 v[196:197], v[188:189], v[216:217] op_sel_hi:[1,0]
	v_pk_mul_f32 v[198:199], v[190:191], v[216:217] op_sel_hi:[1,0]
	v_exp_f32_e32 v196, v196
	v_exp_f32_e32 v197, v197
	v_exp_f32_e32 v198, v198
	v_exp_f32_e32 v199, v199
	v_pk_add_f32 v[196:197], v[196:197], v[214:215] op_sel_hi:[1,0]
	v_pk_add_f32 v[198:199], v[198:199], v[214:215] op_sel_hi:[1,0]
	v_rcp_f32_e32 v196, v196
	v_rcp_f32_e32 v197, v197
	v_rcp_f32_e32 v198, v198
	v_rcp_f32_e32 v199, v199
	v_pk_mul_f32 v[188:189], v[188:189], v[196:197]
	v_pk_mul_f32 v[190:191], v[190:191], v[198:199]
	v_pk_mul_f32 v[188:189], v[188:189], v[192:193]
	v_pk_mul_f32 v[190:191], v[190:191], v[194:195]
	v_cvt_pk_bf16_f32 v152, v188, v189
	v_cvt_pk_bf16_f32 v153, v190, v191
	v_add_u32_e32 v213, 0x58000, v215
	global_store_dwordx4 v213, v[150:153], s[96:97] nt
	v_pk_fma_f32 v[188:189], v[40:41], v[134:135], v[130:131]
	v_pk_fma_f32 v[190:191], v[42:43], v[136:137], v[132:133]
	v_pk_fma_f32 v[192:193], v[32:33], v[204:205], v[208:209]
	v_pk_fma_f32 v[194:195], v[34:35], v[206:207], v[210:211]
	v_cndmask_b32_e64 v48, v40, v48, s[10:11]
	v_cndmask_b32_e64 v49, v41, v49, s[10:11]
	v_cndmask_b32_e64 v50, v42, v50, s[10:11]
	v_cndmask_b32_e64 v51, v43, v51, s[10:11]
	v_cndmask_b32_e64 v36, v32, v36, s[10:11]
	v_cndmask_b32_e64 v37, v33, v37, s[10:11]
	v_cndmask_b32_e64 v38, v34, v38, s[10:11]
	v_cndmask_b32_e64 v39, v35, v39, s[10:11]
	v_fmac_f32_dpp v188, v48, v154 row_ror:2 row_mask:0xf bank_mask:0xf
	v_fmac_f32_dpp v189, v49, v155 row_ror:2 row_mask:0xf bank_mask:0xf
	v_fmac_f32_dpp v190, v50, v156 row_ror:2 row_mask:0xf bank_mask:0xf
	v_fmac_f32_dpp v191, v51, v157 row_ror:2 row_mask:0xf bank_mask:0xf
	v_fmac_f32_dpp v192, v36, v118 row_ror:2 row_mask:0xf bank_mask:0xf
	v_fmac_f32_dpp v193, v37, v119 row_ror:2 row_mask:0xf bank_mask:0xf
	v_fmac_f32_dpp v194, v38, v120 row_ror:2 row_mask:0xf bank_mask:0xf
	v_fmac_f32_dpp v195, v39, v121 row_ror:2 row_mask:0xf bank_mask:0xf
	v_cndmask_b32_e64 v48, v40, v48, s[8:9]
	v_cndmask_b32_e64 v49, v41, v49, s[8:9]
	v_cndmask_b32_e64 v50, v42, v50, s[8:9]
	v_cndmask_b32_e64 v51, v43, v51, s[8:9]
	v_cndmask_b32_e64 v36, v32, v36, s[8:9]
	v_cndmask_b32_e64 v37, v33, v37, s[8:9]
	v_cndmask_b32_e64 v38, v34, v38, s[8:9]
	v_cndmask_b32_e64 v39, v35, v39, s[8:9]
	v_fmac_f32_dpp v188, v48, v142 row_ror:1 row_mask:0xf bank_mask:0xf
	v_fmac_f32_dpp v189, v49, v143 row_ror:1 row_mask:0xf bank_mask:0xf
	v_fmac_f32_dpp v190, v50, v144 row_ror:1 row_mask:0xf bank_mask:0xf
	v_fmac_f32_dpp v191, v51, v145 row_ror:1 row_mask:0xf bank_mask:0xf
	v_fmac_f32_dpp v192, v36, v110 row_ror:1 row_mask:0xf bank_mask:0xf
	v_fmac_f32_dpp v193, v37, v111 row_ror:1 row_mask:0xf bank_mask:0xf
	v_fmac_f32_dpp v194, v38, v112 row_ror:1 row_mask:0xf bank_mask:0xf
	v_fmac_f32_dpp v195, v39, v113 row_ror:1 row_mask:0xf bank_mask:0xf
	v_pk_mul_f32 v[196:197], v[188:189], v[216:217] op_sel_hi:[1,0]
	v_pk_mul_f32 v[198:199], v[190:191], v[216:217] op_sel_hi:[1,0]
	v_exp_f32_e32 v196, v196
	v_exp_f32_e32 v197, v197
	v_exp_f32_e32 v198, v198
	v_exp_f32_e32 v199, v199
	v_pk_add_f32 v[196:197], v[196:197], v[214:215] op_sel_hi:[1,0]
	v_pk_add_f32 v[198:199], v[198:199], v[214:215] op_sel_hi:[1,0]
	v_rcp_f32_e32 v196, v196
	v_rcp_f32_e32 v197, v197
	v_rcp_f32_e32 v198, v198
	v_rcp_f32_e32 v199, v199
	v_pk_mul_f32 v[188:189], v[188:189], v[196:197]
	v_pk_mul_f32 v[190:191], v[190:191], v[198:199]
	v_pk_mul_f32 v[188:189], v[188:189], v[192:193]
	v_pk_mul_f32 v[190:191], v[190:191], v[194:195]
	v_cvt_pk_bf16_f32 v148, v188, v189
	v_cvt_pk_bf16_f32 v149, v190, v191
	v_add_u32_e32 v213, 0x84000, v215
	global_store_dwordx4 v213, v[146:149], s[96:97] nt
	v_pk_fma_f32 v[188:189], v[28:29], v[134:135], v[130:131]
	v_pk_fma_f32 v[190:191], v[30:31], v[136:137], v[132:133]
	v_pk_fma_f32 v[192:193], v[16:17], v[204:205], v[208:209]
	v_pk_fma_f32 v[194:195], v[18:19], v[206:207], v[210:211]
	v_cndmask_b32_e64 v40, v28, v40, s[10:11]
	v_cndmask_b32_e64 v41, v29, v41, s[10:11]
	v_cndmask_b32_e64 v42, v30, v42, s[10:11]
	v_cndmask_b32_e64 v43, v31, v43, s[10:11]
	v_cndmask_b32_e64 v32, v16, v32, s[10:11]
	v_cndmask_b32_e64 v33, v17, v33, s[10:11]
	v_cndmask_b32_e64 v34, v18, v34, s[10:11]
	v_cndmask_b32_e64 v35, v19, v35, s[10:11]
	v_fmac_f32_dpp v188, v40, v154 row_ror:2 row_mask:0xf bank_mask:0xf
	v_fmac_f32_dpp v189, v41, v155 row_ror:2 row_mask:0xf bank_mask:0xf
	v_fmac_f32_dpp v190, v42, v156 row_ror:2 row_mask:0xf bank_mask:0xf
	v_fmac_f32_dpp v191, v43, v157 row_ror:2 row_mask:0xf bank_mask:0xf
	v_fmac_f32_dpp v192, v32, v118 row_ror:2 row_mask:0xf bank_mask:0xf
	v_fmac_f32_dpp v193, v33, v119 row_ror:2 row_mask:0xf bank_mask:0xf
	v_fmac_f32_dpp v194, v34, v120 row_ror:2 row_mask:0xf bank_mask:0xf
	v_fmac_f32_dpp v195, v35, v121 row_ror:2 row_mask:0xf bank_mask:0xf
	v_cndmask_b32_e64 v40, v28, v40, s[8:9]
	v_cndmask_b32_e64 v41, v29, v41, s[8:9]
	v_cndmask_b32_e64 v42, v30, v42, s[8:9]
	v_cndmask_b32_e64 v43, v31, v43, s[8:9]
	v_cndmask_b32_e64 v32, v16, v32, s[8:9]
	v_cndmask_b32_e64 v33, v17, v33, s[8:9]
	v_cndmask_b32_e64 v34, v18, v34, s[8:9]
	v_cndmask_b32_e64 v35, v19, v35, s[8:9]
	v_fmac_f32_dpp v188, v40, v142 row_ror:1 row_mask:0xf bank_mask:0xf
	v_fmac_f32_dpp v189, v41, v143 row_ror:1 row_mask:0xf bank_mask:0xf
	v_fmac_f32_dpp v190, v42, v144 row_ror:1 row_mask:0xf bank_mask:0xf
	v_fmac_f32_dpp v191, v43, v145 row_ror:1 row_mask:0xf bank_mask:0xf
	v_fmac_f32_dpp v192, v32, v110 row_ror:1 row_mask:0xf bank_mask:0xf
	v_fmac_f32_dpp v193, v33, v111 row_ror:1 row_mask:0xf bank_mask:0xf
	v_fmac_f32_dpp v194, v34, v112 row_ror:1 row_mask:0xf bank_mask:0xf
	v_fmac_f32_dpp v195, v35, v113 row_ror:1 row_mask:0xf bank_mask:0xf
	v_pk_mul_f32 v[196:197], v[188:189], v[216:217] op_sel_hi:[1,0]
	v_pk_mul_f32 v[198:199], v[190:191], v[216:217] op_sel_hi:[1,0]
	v_exp_f32_e32 v196, v196
	v_exp_f32_e32 v197, v197
	v_exp_f32_e32 v198, v198
	v_exp_f32_e32 v199, v199
	v_pk_add_f32 v[196:197], v[196:197], v[214:215] op_sel_hi:[1,0]
	v_pk_add_f32 v[198:199], v[198:199], v[214:215] op_sel_hi:[1,0]
	v_rcp_f32_e32 v196, v196
	v_rcp_f32_e32 v197, v197
	v_rcp_f32_e32 v198, v198
	v_rcp_f32_e32 v199, v199
	v_pk_mul_f32 v[188:189], v[188:189], v[196:197]
	v_pk_mul_f32 v[190:191], v[190:191], v[198:199]
	v_pk_mul_f32 v[188:189], v[188:189], v[192:193]
	v_pk_mul_f32 v[190:191], v[190:191], v[194:195]
	v_cvt_pk_bf16_f32 v140, v188, v189
	v_cvt_pk_bf16_f32 v141, v190, v191
	v_add_u32_e32 v213, 0xb0000, v215
	global_store_dwordx4 v213, v[138:141], s[96:97] nt
	v_pk_fma_f32 v[188:189], v[24:25], v[134:135], v[130:131]
	v_pk_fma_f32 v[190:191], v[26:27], v[136:137], v[132:133]
	v_pk_fma_f32 v[192:193], v[12:13], v[204:205], v[208:209]
	v_pk_fma_f32 v[194:195], v[14:15], v[206:207], v[210:211]
	v_cndmask_b32_e64 v28, v24, v28, s[10:11]
	v_cndmask_b32_e64 v29, v25, v29, s[10:11]
	v_cndmask_b32_e64 v30, v26, v30, s[10:11]
	v_cndmask_b32_e64 v31, v27, v31, s[10:11]
	v_cndmask_b32_e64 v16, v12, v16, s[10:11]
	v_cndmask_b32_e64 v17, v13, v17, s[10:11]
	v_cndmask_b32_e64 v18, v14, v18, s[10:11]
	v_cndmask_b32_e64 v19, v15, v19, s[10:11]
	v_fmac_f32_dpp v188, v28, v154 row_ror:2 row_mask:0xf bank_mask:0xf
	v_fmac_f32_dpp v189, v29, v155 row_ror:2 row_mask:0xf bank_mask:0xf
	v_fmac_f32_dpp v190, v30, v156 row_ror:2 row_mask:0xf bank_mask:0xf
	v_fmac_f32_dpp v191, v31, v157 row_ror:2 row_mask:0xf bank_mask:0xf
	v_fmac_f32_dpp v192, v16, v118 row_ror:2 row_mask:0xf bank_mask:0xf
	v_fmac_f32_dpp v193, v17, v119 row_ror:2 row_mask:0xf bank_mask:0xf
	v_fmac_f32_dpp v194, v18, v120 row_ror:2 row_mask:0xf bank_mask:0xf
	v_fmac_f32_dpp v195, v19, v121 row_ror:2 row_mask:0xf bank_mask:0xf
	v_cndmask_b32_e64 v28, v24, v28, s[8:9]
	v_cndmask_b32_e64 v29, v25, v29, s[8:9]
	v_cndmask_b32_e64 v30, v26, v30, s[8:9]
	v_cndmask_b32_e64 v31, v27, v31, s[8:9]
	v_cndmask_b32_e64 v16, v12, v16, s[8:9]
	v_cndmask_b32_e64 v17, v13, v17, s[8:9]
	v_cndmask_b32_e64 v18, v14, v18, s[8:9]
	v_cndmask_b32_e64 v19, v15, v19, s[8:9]
	v_fmac_f32_dpp v188, v28, v142 row_ror:1 row_mask:0xf bank_mask:0xf
	v_fmac_f32_dpp v189, v29, v143 row_ror:1 row_mask:0xf bank_mask:0xf
	v_fmac_f32_dpp v190, v30, v144 row_ror:1 row_mask:0xf bank_mask:0xf
	v_fmac_f32_dpp v191, v31, v145 row_ror:1 row_mask:0xf bank_mask:0xf
	v_fmac_f32_dpp v192, v16, v110 row_ror:1 row_mask:0xf bank_mask:0xf
	v_fmac_f32_dpp v193, v17, v111 row_ror:1 row_mask:0xf bank_mask:0xf
	v_fmac_f32_dpp v194, v18, v112 row_ror:1 row_mask:0xf bank_mask:0xf
	v_fmac_f32_dpp v195, v19, v113 row_ror:1 row_mask:0xf bank_mask:0xf
	v_pk_mul_f32 v[196:197], v[188:189], v[216:217] op_sel_hi:[1,0]
	v_pk_mul_f32 v[198:199], v[190:191], v[216:217] op_sel_hi:[1,0]
	v_exp_f32_e32 v196, v196
	v_exp_f32_e32 v197, v197
	v_exp_f32_e32 v198, v198
	v_exp_f32_e32 v199, v199
	v_pk_add_f32 v[196:197], v[196:197], v[214:215] op_sel_hi:[1,0]
	v_pk_add_f32 v[198:199], v[198:199], v[214:215] op_sel_hi:[1,0]
	v_rcp_f32_e32 v196, v196
	v_rcp_f32_e32 v197, v197
	v_rcp_f32_e32 v198, v198
	v_rcp_f32_e32 v199, v199
	v_pk_mul_f32 v[188:189], v[188:189], v[196:197]
	v_pk_mul_f32 v[190:191], v[190:191], v[198:199]
	v_pk_mul_f32 v[188:189], v[188:189], v[192:193]
	v_pk_mul_f32 v[190:191], v[190:191], v[194:195]
	v_cvt_pk_bf16_f32 v128, v188, v189
	v_cvt_pk_bf16_f32 v129, v190, v191
	v_add_u32_e32 v213, 0xdc000, v215
	global_store_dwordx4 v213, v[126:129], s[96:97] nt
	v_pk_fma_f32 v[188:189], v[20:21], v[134:135], v[130:131]
	v_pk_fma_f32 v[190:191], v[22:23], v[136:137], v[132:133]
	v_pk_fma_f32 v[192:193], v[8:9], v[204:205], v[208:209]
	v_pk_fma_f32 v[194:195], v[10:11], v[206:207], v[210:211]
	v_cndmask_b32_e64 v24, v20, v24, s[10:11]
	v_cndmask_b32_e64 v25, v21, v25, s[10:11]
	v_cndmask_b32_e64 v26, v22, v26, s[10:11]
	v_cndmask_b32_e64 v27, v23, v27, s[10:11]
	v_cndmask_b32_e64 v12, v8, v12, s[10:11]
	v_cndmask_b32_e64 v13, v9, v13, s[10:11]
	v_cndmask_b32_e64 v14, v10, v14, s[10:11]
	v_cndmask_b32_e64 v15, v11, v15, s[10:11]
	v_fmac_f32_dpp v188, v24, v154 row_ror:2 row_mask:0xf bank_mask:0xf
	v_fmac_f32_dpp v189, v25, v155 row_ror:2 row_mask:0xf bank_mask:0xf
	v_fmac_f32_dpp v190, v26, v156 row_ror:2 row_mask:0xf bank_mask:0xf
	v_fmac_f32_dpp v191, v27, v157 row_ror:2 row_mask:0xf bank_mask:0xf
	v_fmac_f32_dpp v192, v12, v118 row_ror:2 row_mask:0xf bank_mask:0xf
	v_fmac_f32_dpp v193, v13, v119 row_ror:2 row_mask:0xf bank_mask:0xf
	v_fmac_f32_dpp v194, v14, v120 row_ror:2 row_mask:0xf bank_mask:0xf
	v_fmac_f32_dpp v195, v15, v121 row_ror:2 row_mask:0xf bank_mask:0xf
	v_cndmask_b32_e64 v24, v20, v24, s[8:9]
	v_cndmask_b32_e64 v25, v21, v25, s[8:9]
	v_cndmask_b32_e64 v26, v22, v26, s[8:9]
	v_cndmask_b32_e64 v27, v23, v27, s[8:9]
	v_cndmask_b32_e64 v12, v8, v12, s[8:9]
	v_cndmask_b32_e64 v13, v9, v13, s[8:9]
	v_cndmask_b32_e64 v14, v10, v14, s[8:9]
	v_cndmask_b32_e64 v15, v11, v15, s[8:9]
	v_fmac_f32_dpp v188, v24, v142 row_ror:1 row_mask:0xf bank_mask:0xf
	v_fmac_f32_dpp v189, v25, v143 row_ror:1 row_mask:0xf bank_mask:0xf
	v_fmac_f32_dpp v190, v26, v144 row_ror:1 row_mask:0xf bank_mask:0xf
	v_fmac_f32_dpp v191, v27, v145 row_ror:1 row_mask:0xf bank_mask:0xf
	v_fmac_f32_dpp v192, v12, v110 row_ror:1 row_mask:0xf bank_mask:0xf
	v_fmac_f32_dpp v193, v13, v111 row_ror:1 row_mask:0xf bank_mask:0xf
	v_fmac_f32_dpp v194, v14, v112 row_ror:1 row_mask:0xf bank_mask:0xf
	v_fmac_f32_dpp v195, v15, v113 row_ror:1 row_mask:0xf bank_mask:0xf
	v_pk_mul_f32 v[196:197], v[188:189], v[216:217] op_sel_hi:[1,0]
	v_pk_mul_f32 v[198:199], v[190:191], v[216:217] op_sel_hi:[1,0]
	v_exp_f32_e32 v196, v196
	v_exp_f32_e32 v197, v197
	v_exp_f32_e32 v198, v198
	v_exp_f32_e32 v199, v199
	v_pk_add_f32 v[196:197], v[196:197], v[214:215] op_sel_hi:[1,0]
	v_pk_add_f32 v[198:199], v[198:199], v[214:215] op_sel_hi:[1,0]
	v_rcp_f32_e32 v196, v196
	v_rcp_f32_e32 v197, v197
	v_rcp_f32_e32 v198, v198
	v_rcp_f32_e32 v199, v199
	v_pk_mul_f32 v[188:189], v[188:189], v[196:197]
	v_pk_mul_f32 v[190:191], v[190:191], v[198:199]
	v_pk_mul_f32 v[188:189], v[188:189], v[192:193]
	v_pk_mul_f32 v[190:191], v[190:191], v[194:195]
	v_cvt_pk_bf16_f32 v124, v188, v189
	v_cvt_pk_bf16_f32 v125, v190, v191
	v_add_u32_e32 v213, 0x108000, v215
	global_store_dwordx4 v213, v[122:125], s[96:97] nt
	v_pk_fma_f32 v[188:189], v[4:5], v[134:135], v[130:131]
	v_pk_fma_f32 v[190:191], v[6:7], v[136:137], v[132:133]
	v_pk_fma_f32 v[192:193], v[0:1], v[204:205], v[208:209]
	v_pk_fma_f32 v[194:195], v[2:3], v[206:207], v[210:211]
	v_cndmask_b32_e64 v20, v4, v20, s[10:11]
	v_cndmask_b32_e64 v21, v5, v21, s[10:11]
	v_cndmask_b32_e64 v22, v6, v22, s[10:11]
	v_cndmask_b32_e64 v23, v7, v23, s[10:11]
	v_cndmask_b32_e64 v8, v0, v8, s[10:11]
	v_cndmask_b32_e64 v9, v1, v9, s[10:11]
	v_cndmask_b32_e64 v10, v2, v10, s[10:11]
	v_cndmask_b32_e64 v11, v3, v11, s[10:11]
	v_fmac_f32_dpp v188, v20, v154 row_ror:2 row_mask:0xf bank_mask:0xf
	v_fmac_f32_dpp v189, v21, v155 row_ror:2 row_mask:0xf bank_mask:0xf
	v_fmac_f32_dpp v190, v22, v156 row_ror:2 row_mask:0xf bank_mask:0xf
	v_fmac_f32_dpp v191, v23, v157 row_ror:2 row_mask:0xf bank_mask:0xf
	v_fmac_f32_dpp v192, v8, v118 row_ror:2 row_mask:0xf bank_mask:0xf
	v_fmac_f32_dpp v193, v9, v119 row_ror:2 row_mask:0xf bank_mask:0xf
	v_fmac_f32_dpp v194, v10, v120 row_ror:2 row_mask:0xf bank_mask:0xf
	v_fmac_f32_dpp v195, v11, v121 row_ror:2 row_mask:0xf bank_mask:0xf
	v_cndmask_b32_e64 v20, v4, v20, s[8:9]
	v_cndmask_b32_e64 v21, v5, v21, s[8:9]
	v_cndmask_b32_e64 v22, v6, v22, s[8:9]
	v_cndmask_b32_e64 v23, v7, v23, s[8:9]
	v_cndmask_b32_e64 v8, v0, v8, s[8:9]
	v_cndmask_b32_e64 v9, v1, v9, s[8:9]
	v_cndmask_b32_e64 v10, v2, v10, s[8:9]
	v_cndmask_b32_e64 v11, v3, v11, s[8:9]
	v_fmac_f32_dpp v188, v20, v142 row_ror:1 row_mask:0xf bank_mask:0xf
	v_fmac_f32_dpp v189, v21, v143 row_ror:1 row_mask:0xf bank_mask:0xf
	v_fmac_f32_dpp v190, v22, v144 row_ror:1 row_mask:0xf bank_mask:0xf
	v_fmac_f32_dpp v191, v23, v145 row_ror:1 row_mask:0xf bank_mask:0xf
	v_fmac_f32_dpp v192, v8, v110 row_ror:1 row_mask:0xf bank_mask:0xf
	v_fmac_f32_dpp v193, v9, v111 row_ror:1 row_mask:0xf bank_mask:0xf
	v_fmac_f32_dpp v194, v10, v112 row_ror:1 row_mask:0xf bank_mask:0xf
	v_fmac_f32_dpp v195, v11, v113 row_ror:1 row_mask:0xf bank_mask:0xf
	v_pk_mul_f32 v[196:197], v[188:189], v[216:217] op_sel_hi:[1,0]
	v_pk_mul_f32 v[198:199], v[190:191], v[216:217] op_sel_hi:[1,0]
	v_exp_f32_e32 v196, v196
	v_exp_f32_e32 v197, v197
	v_exp_f32_e32 v198, v198
	v_exp_f32_e32 v199, v199
	v_pk_add_f32 v[196:197], v[196:197], v[214:215] op_sel_hi:[1,0]
	v_pk_add_f32 v[198:199], v[198:199], v[214:215] op_sel_hi:[1,0]
	v_rcp_f32_e32 v196, v196
	v_rcp_f32_e32 v197, v197
	v_rcp_f32_e32 v198, v198
	v_rcp_f32_e32 v199, v199
	v_pk_mul_f32 v[188:189], v[188:189], v[196:197]
	v_pk_mul_f32 v[190:191], v[190:191], v[198:199]
	v_pk_mul_f32 v[188:189], v[188:189], v[192:193]
	v_pk_mul_f32 v[190:191], v[190:191], v[194:195]
	v_cvt_pk_bf16_f32 v116, v188, v189
	v_cvt_pk_bf16_f32 v117, v190, v191
	v_add_u32_e32 v213, 0x134000, v215
	global_store_dwordx4 v213, v[114:117], s[96:97] nt
	s_branch .LBB0_359

.Lst_out_s8:
	s_lshl_b32 s8, s0, 8
	s_add_i32 s8, s8, s58
	s_lshl_b32 s9, s1, 7
	s_add_i32 s9, s9, s53
	s_lshl_b32 s10, s0, 3
	s_lshr_b32 s11, s58, 5
	s_add_i32 s10, s10, s11
	v_add_u32_e32 v200, s8, v163
	v_lshlrev_b32_e32 v213, 2, v200
	global_load_dword v188, v213, s[4:5]
	global_load_dword v189, v213, s[4:5] offset:64
	global_load_dword v190, v213, s[4:5] offset:128
	global_load_dword v191, v213, s[4:5] offset:192
	global_load_dword v192, v213, s[4:5] offset:256
	global_load_dword v193, v213, s[4:5] offset:320
	global_load_dword v194, v213, s[4:5] offset:384
	global_load_dword v195, v213, s[4:5] offset:448
	v_lshl_add_u32 v201, v225, 3, s9
	v_lshlrev_b32_e32 v212, 2, v201
	v_add_u32_e32 v213, 0x21000, v212
	global_load_dwordx4 v[76:79], v213, s[82:83]
	v_add_u32_e32 v213, 0x2c000, v212
	global_load_dwordx4 v[80:83], v213, s[82:83]
	v_add_u32_e32 v213, 0x37000, v212
	global_load_dwordx4 v[84:87], v213, s[82:83]
	v_add_u32_e32 v213, 0xb000, v212
	global_load_dwordx4 v[88:91], v213, s[84:85]
	v_add_u32_e32 v213, 0x26800, v212
	global_load_dwordx4 v[92:95], v213, s[82:83]
	v_add_u32_e32 v213, 0x31800, v212
	global_load_dwordx4 v[96:99], v213, s[82:83]
	v_add_u32_e32 v213, 0x3c800, v212
	global_load_dwordx4 v[100:103], v213, s[82:83]
	v_add_u32_e32 v213, 0x10800, v212
	global_load_dwordx4 v[104:107], v213, s[84:85]
	v_mul_u32_u24_e32 v215, 0x2c00, v200
	v_lshl_add_u32 v215, v201, 1, v215
	v_add_u32_e32 v213, s10, v163
	v_mul_u32_u24_e32 v217, 0xb000, v213
	v_add_u32_e32 v217, v217, v212
	v_cmp_gt_u32_e64 s[8:9], 2, v163
	v_cmp_lt_u32_e64 s[10:11], 13, v163
	v_cmp_lt_u32_e32 vcc, 1, v163
	v_mov_b32_e32 v214, 1.0
	v_mov_b32_e32 v216, 0xbfb8aa3b
	v_mov_b32_e32 v108, 0x3727c5ac
	s_waitcnt vmcnt(8)
	v_fmamk_f32 v188, v188, 0x3a000000, v108
	v_fmamk_f32 v189, v189, 0x3a000000, v108
	v_fmamk_f32 v190, v190, 0x3a000000, v108
	v_fmamk_f32 v191, v191, 0x3a000000, v108
	v_fmamk_f32 v192, v192, 0x3a000000, v108
	v_fmamk_f32 v193, v193, 0x3a000000, v108
	v_fmamk_f32 v194, v194, 0x3a000000, v108
	v_fmamk_f32 v195, v195, 0x3a000000, v108
	v_rsq_f32_e32 v188, v188
	v_rsq_f32_e32 v189, v189
	v_rsq_f32_e32 v190, v190
	v_rsq_f32_e32 v191, v191
	v_rsq_f32_e32 v192, v192
	v_rsq_f32_e32 v193, v193
	v_rsq_f32_e32 v194, v194
	v_rsq_f32_e32 v195, v195
	v_pk_mul_f32 v[158:159], v[158:159], v[188:189] op_sel_hi:[1,0]
	v_pk_mul_f32 v[160:161], v[160:161], v[188:189] op_sel_hi:[1,0]
	v_pk_mul_f32 v[60:61], v[60:61], v[188:189] op_sel_hi:[1,0]
	v_pk_mul_f32 v[62:63], v[62:63], v[188:189] op_sel_hi:[1,0]
	v_pk_mul_f32 v[154:155], v[154:155], v[188:189] op_sel_hi:[1,0]
	v_pk_mul_f32 v[156:157], v[156:157], v[188:189] op_sel_hi:[1,0]
	v_pk_mul_f32 v[56:57], v[56:57], v[188:189] op_sel_hi:[1,0]
	v_pk_mul_f32 v[58:59], v[58:59], v[188:189] op_sel_hi:[1,0]
	v_pk_mul_f32 v[150:151], v[150:151], v[188:189] op_sel:[0,1] op_sel_hi:[1,1]
	v_pk_mul_f32 v[152:153], v[152:153], v[188:189] op_sel:[0,1] op_sel_hi:[1,1]
	v_pk_mul_f32 v[52:53], v[52:53], v[188:189] op_sel:[0,1] op_sel_hi:[1,1]
	v_pk_mul_f32 v[54:55], v[54:55], v[188:189] op_sel:[0,1] op_sel_hi:[1,1]
	v_pk_mul_f32 v[142:143], v[142:143], v[188:189] op_sel:[0,1] op_sel_hi:[1,1]
	v_pk_mul_f32 v[144:145], v[144:145], v[188:189] op_sel:[0,1] op_sel_hi:[1,1]
	v_pk_mul_f32 v[44:45], v[44:45], v[188:189] op_sel:[0,1] op_sel_hi:[1,1]
	v_pk_mul_f32 v[46:47], v[46:47], v[188:189] op_sel:[0,1] op_sel_hi:[1,1]
	v_pk_mul_f32 v[146:147], v[146:147], v[190:191] op_sel_hi:[1,0]
	v_pk_mul_f32 v[148:149], v[148:149], v[190:191] op_sel_hi:[1,0]
	v_pk_mul_f32 v[48:49], v[48:49], v[190:191] op_sel_hi:[1,0]
	v_pk_mul_f32 v[50:51], v[50:51], v[190:191] op_sel_hi:[1,0]
	v_pk_mul_f32 v[134:135], v[134:135], v[190:191] op_sel_hi:[1,0]
	v_pk_mul_f32 v[136:137], v[136:137], v[190:191] op_sel_hi:[1,0]
	v_pk_mul_f32 v[36:37], v[36:37], v[190:191] op_sel_hi:[1,0]
	v_pk_mul_f32 v[38:39], v[38:39], v[190:191] op_sel_hi:[1,0]
	v_pk_mul_f32 v[138:139], v[138:139], v[190:191] op_sel:[0,1] op_sel_hi:[1,1]
	v_pk_mul_f32 v[140:141], v[140:141], v[190:191] op_sel:[0,1] op_sel_hi:[1,1]
	v_pk_mul_f32 v[40:41], v[40:41], v[190:191] op_sel:[0,1] op_sel_hi:[1,1]
	v_pk_mul_f32 v[42:43], v[42:43], v[190:191] op_sel:[0,1] op_sel_hi:[1,1]
	v_pk_mul_f32 v[130:131], v[130:131], v[190:191] op_sel:[0,1] op_sel_hi:[1,1]
	v_pk_mul_f32 v[132:133], v[132:133], v[190:191] op_sel:[0,1] op_sel_hi:[1,1]
	v_pk_mul_f32 v[32:33], v[32:33], v[190:191] op_sel:[0,1] op_sel_hi:[1,1]
	v_pk_mul_f32 v[34:35], v[34:35], v[190:191] op_sel:[0,1] op_sel_hi:[1,1]
	v_pk_mul_f32 v[126:127], v[126:127], v[192:193] op_sel_hi:[1,0]
	v_pk_mul_f32 v[128:129], v[128:129], v[192:193] op_sel_hi:[1,0]
	v_pk_mul_f32 v[28:29], v[28:29], v[192:193] op_sel_hi:[1,0]
	v_pk_mul_f32 v[30:31], v[30:31], v[192:193] op_sel_hi:[1,0]
	v_pk_mul_f32 v[118:119], v[118:119], v[192:193] op_sel_hi:[1,0]
	v_pk_mul_f32 v[120:121], v[120:121], v[192:193] op_sel_hi:[1,0]
	v_pk_mul_f32 v[16:17], v[16:17], v[192:193] op_sel_hi:[1,0]
	v_pk_mul_f32 v[18:19], v[18:19], v[192:193] op_sel_hi:[1,0]
	v_pk_mul_f32 v[122:123], v[122:123], v[192:193] op_sel:[0,1] op_sel_hi:[1,1]
	v_pk_mul_f32 v[124:125], v[124:125], v[192:193] op_sel:[0,1] op_sel_hi:[1,1]
	v_pk_mul_f32 v[24:25], v[24:25], v[192:193] op_sel:[0,1] op_sel_hi:[1,1]
	v_pk_mul_f32 v[26:27], v[26:27], v[192:193] op_sel:[0,1] op_sel_hi:[1,1]
	v_pk_mul_f32 v[110:111], v[110:111], v[192:193] op_sel:[0,1] op_sel_hi:[1,1]
	v_pk_mul_f32 v[112:113], v[112:113], v[192:193] op_sel:[0,1] op_sel_hi:[1,1]
	v_pk_mul_f32 v[12:13], v[12:13], v[192:193] op_sel:[0,1] op_sel_hi:[1,1]
	v_pk_mul_f32 v[14:15], v[14:15], v[192:193] op_sel:[0,1] op_sel_hi:[1,1]
	v_pk_mul_f32 v[114:115], v[114:115], v[194:195] op_sel_hi:[1,0]
	v_pk_mul_f32 v[116:117], v[116:117], v[194:195] op_sel_hi:[1,0]
	v_pk_mul_f32 v[20:21], v[20:21], v[194:195] op_sel_hi:[1,0]
	v_pk_mul_f32 v[22:23], v[22:23], v[194:195] op_sel_hi:[1,0]
	v_pk_mul_f32 v[68:69], v[68:69], v[194:195] op_sel_hi:[1,0]
	v_pk_mul_f32 v[70:71], v[70:71], v[194:195] op_sel_hi:[1,0]
	v_pk_mul_f32 v[8:9], v[8:9], v[194:195] op_sel_hi:[1,0]
	v_pk_mul_f32 v[10:11], v[10:11], v[194:195] op_sel_hi:[1,0]
	v_pk_mul_f32 v[72:73], v[72:73], v[194:195] op_sel:[0,1] op_sel_hi:[1,1]
	v_pk_mul_f32 v[74:75], v[74:75], v[194:195] op_sel:[0,1] op_sel_hi:[1,1]
	v_pk_mul_f32 v[4:5], v[4:5], v[194:195] op_sel:[0,1] op_sel_hi:[1,1]
	v_pk_mul_f32 v[6:7], v[6:7], v[194:195] op_sel:[0,1] op_sel_hi:[1,1]
	v_pk_mul_f32 v[64:65], v[64:65], v[194:195] op_sel:[0,1] op_sel_hi:[1,1]
	v_pk_mul_f32 v[66:67], v[66:67], v[194:195] op_sel:[0,1] op_sel_hi:[1,1]
	v_pk_mul_f32 v[0:1], v[0:1], v[194:195] op_sel:[0,1] op_sel_hi:[1,1]
	v_pk_mul_f32 v[2:3], v[2:3], v[194:195] op_sel:[0,1] op_sel_hi:[1,1]
	s_nop 1
	s_mov_b64 exec, s[8:9]
	v_add_u32_e32 v213, 0x5800, v217
	global_store_dwordx4 v217, v[158:161], s[70:71]
	global_store_dwordx4 v213, v[154:157], s[70:71]
	global_store_dwordx4 v217, v[60:63], s[70:71] offset:16
	global_store_dwordx4 v213, v[56:59], s[70:71] offset:16
	s_mov_b64 exec, s[10:11]
	v_add_u32_e32 v213, 0xfff7c000, v217
	global_store_dwordx4 v213, v[72:75], s[70:71]
	global_store_dwordx4 v213, v[4:7], s[70:71] offset:16
	v_add_u32_e32 v213, 0xfff81800, v217
	global_store_dwordx4 v213, v[64:67], s[70:71]
	global_store_dwordx4 v213, v[0:3], s[70:71] offset:16
	s_mov_b64 exec, -1
	v_cmp_eq_u32_e64 s[8:9], 15, v163
	v_add_u32_e32 v213, 0x3c800, v212
	global_load_dwordx4 v[204:207], v213, s[82:83] offset:16
	v_add_u32_e32 v213, 0x10800, v212
	global_load_dwordx4 v[208:211], v213, s[84:85] offset:16
	s_waitcnt vmcnt(10)
	v_pk_fma_f32 v[188:189], v[158:159], v[84:85], v[88:89]
	v_pk_fma_f32 v[190:191], v[160:161], v[86:87], v[90:91]
	v_pk_fma_f32 v[192:193], v[154:155], v[100:101], v[104:105]
	v_pk_fma_f32 v[194:195], v[156:157], v[102:103], v[106:107]
	v_fmac_f32_dpp v188, v158, v80 row_shr:1 row_mask:0xf bank_mask:0xf
	v_fmac_f32_dpp v189, v159, v81 row_shr:1 row_mask:0xf bank_mask:0xf
	v_fmac_f32_dpp v190, v160, v82 row_shr:1 row_mask:0xf bank_mask:0xf
	v_fmac_f32_dpp v191, v161, v83 row_shr:1 row_mask:0xf bank_mask:0xf
	v_fmac_f32_dpp v192, v154, v96 row_shr:1 row_mask:0xf bank_mask:0xf
	v_fmac_f32_dpp v193, v155, v97 row_shr:1 row_mask:0xf bank_mask:0xf
	v_fmac_f32_dpp v194, v156, v98 row_shr:1 row_mask:0xf bank_mask:0xf
	v_fmac_f32_dpp v195, v157, v99 row_shr:1 row_mask:0xf bank_mask:0xf
	v_fmac_f32_dpp v188, v158, v76 row_shr:2 row_mask:0xf bank_mask:0xf
	v_fmac_f32_dpp v189, v159, v77 row_shr:2 row_mask:0xf bank_mask:0xf
	v_fmac_f32_dpp v190, v160, v78 row_shr:2 row_mask:0xf bank_mask:0xf
	v_fmac_f32_dpp v191, v161, v79 row_shr:2 row_mask:0xf bank_mask:0xf
	v_fmac_f32_dpp v192, v154, v92 row_shr:2 row_mask:0xf bank_mask:0xf
	v_fmac_f32_dpp v193, v155, v93 row_shr:2 row_mask:0xf bank_mask:0xf
	v_fmac_f32_dpp v194, v156, v94 row_shr:2 row_mask:0xf bank_mask:0xf
	v_fmac_f32_dpp v195, v157, v95 row_shr:2 row_mask:0xf bank_mask:0xf
	v_pk_mul_f32 v[196:197], v[188:189], v[216:217] op_sel_hi:[1,0]
	v_pk_mul_f32 v[198:199], v[190:191], v[216:217] op_sel_hi:[1,0]
	v_exp_f32_e32 v196, v196
	v_exp_f32_e32 v197, v197
	v_exp_f32_e32 v198, v198
	v_exp_f32_e32 v199, v199
	v_pk_add_f32 v[196:197], v[196:197], v[214:215] op_sel_hi:[1,0]
	v_pk_add_f32 v[198:199], v[198:199], v[214:215] op_sel_hi:[1,0]
	v_rcp_f32_e32 v196, v196
	v_rcp_f32_e32 v197, v197
	v_rcp_f32_e32 v198, v198
	v_rcp_f32_e32 v199, v199
	v_pk_mul_f32 v[188:189], v[188:189], v[196:197]
	v_pk_mul_f32 v[190:191], v[190:191], v[198:199]
	v_pk_mul_f32 v[188:189], v[188:189], v[192:193]
	v_pk_mul_f32 v[190:191], v[190:191], v[194:195]
	v_cvt_pk_bf16_f32 v200, v188, v189
	v_cvt_pk_bf16_f32 v201, v190, v191
	v_pk_fma_f32 v[188:189], v[150:151], v[84:85], v[88:89]
	v_pk_fma_f32 v[190:191], v[152:153], v[86:87], v[90:91]
	v_pk_fma_f32 v[192:193], v[142:143], v[100:101], v[104:105]
	v_pk_fma_f32 v[194:195], v[144:145], v[102:103], v[106:107]
	v_cndmask_b32_e64 v158, v150, v158, s[10:11]
	v_cndmask_b32_e64 v159, v151, v159, s[10:11]
	v_cndmask_b32_e64 v160, v152, v160, s[10:11]
	v_cndmask_b32_e64 v161, v153, v161, s[10:11]
	v_cndmask_b32_e64 v154, v142, v154, s[10:11]
	v_cndmask_b32_e64 v155, v143, v155, s[10:11]
	v_cndmask_b32_e64 v156, v144, v156, s[10:11]
	v_cndmask_b32_e64 v157, v145, v157, s[10:11]
	v_fmac_f32_dpp v188, v158, v76 row_ror:2 row_mask:0xf bank_mask:0xf
	v_fmac_f32_dpp v189, v159, v77 row_ror:2 row_mask:0xf bank_mask:0xf
	v_fmac_f32_dpp v190, v160, v78 row_ror:2 row_mask:0xf bank_mask:0xf
	v_fmac_f32_dpp v191, v161, v79 row_ror:2 row_mask:0xf bank_mask:0xf
	v_fmac_f32_dpp v192, v154, v92 row_ror:2 row_mask:0xf bank_mask:0xf
	v_fmac_f32_dpp v193, v155, v93 row_ror:2 row_mask:0xf bank_mask:0xf
	v_fmac_f32_dpp v194, v156, v94 row_ror:2 row_mask:0xf bank_mask:0xf
	v_fmac_f32_dpp v195, v157, v95 row_ror:2 row_mask:0xf bank_mask:0xf
	v_cndmask_b32_e64 v158, v150, v158, s[8:9]
	v_cndmask_b32_e64 v159, v151, v159, s[8:9]
	v_cndmask_b32_e64 v160, v152, v160, s[8:9]
	v_cndmask_b32_e64 v161, v153, v161, s[8:9]
	v_cndmask_b32_e64 v154, v142, v154, s[8:9]
	v_cndmask_b32_e64 v155, v143, v155, s[8:9]
	v_cndmask_b32_e64 v156, v144, v156, s[8:9]
	v_cndmask_b32_e64 v157, v145, v157, s[8:9]
	v_fmac_f32_dpp v188, v158, v80 row_ror:1 row_mask:0xf bank_mask:0xf
	v_fmac_f32_dpp v189, v159, v81 row_ror:1 row_mask:0xf bank_mask:0xf
	v_fmac_f32_dpp v190, v160, v82 row_ror:1 row_mask:0xf bank_mask:0xf
	v_fmac_f32_dpp v191, v161, v83 row_ror:1 row_mask:0xf bank_mask:0xf
	v_fmac_f32_dpp v192, v154, v96 row_ror:1 row_mask:0xf bank_mask:0xf
	v_fmac_f32_dpp v193, v155, v97 row_ror:1 row_mask:0xf bank_mask:0xf
	v_fmac_f32_dpp v194, v156, v98 row_ror:1 row_mask:0xf bank_mask:0xf
	v_fmac_f32_dpp v195, v157, v99 row_ror:1 row_mask:0xf bank_mask:0xf
	v_pk_mul_f32 v[196:197], v[188:189], v[216:217] op_sel_hi:[1,0]
	v_pk_mul_f32 v[198:199], v[190:191], v[216:217] op_sel_hi:[1,0]
	v_exp_f32_e32 v196, v196
	v_exp_f32_e32 v197, v197
	v_exp_f32_e32 v198, v198
	v_exp_f32_e32 v199, v199
	v_pk_add_f32 v[196:197], v[196:197], v[214:215] op_sel_hi:[1,0]
	v_pk_add_f32 v[198:199], v[198:199], v[214:215] op_sel_hi:[1,0]
	v_rcp_f32_e32 v196, v196
	v_rcp_f32_e32 v197, v197
	v_rcp_f32_e32 v198, v198
	v_rcp_f32_e32 v199, v199
	v_pk_mul_f32 v[188:189], v[188:189], v[196:197]
	v_pk_mul_f32 v[190:191], v[190:191], v[198:199]
	v_pk_mul_f32 v[188:189], v[188:189], v[192:193]
	v_pk_mul_f32 v[190:191], v[190:191], v[194:195]
	v_cvt_pk_bf16_f32 v158, v188, v189
	v_cvt_pk_bf16_f32 v159, v190, v191
	v_add_u32_e32 v213, 0x21000, v212
	global_load_dwordx4 v[154:157], v213, s[82:83] offset:16
	v_pk_fma_f32 v[188:189], v[146:147], v[84:85], v[88:89]
	v_pk_fma_f32 v[190:191], v[148:149], v[86:87], v[90:91]
	v_pk_fma_f32 v[192:193], v[134:135], v[100:101], v[104:105]
	v_pk_fma_f32 v[194:195], v[136:137], v[102:103], v[106:107]
	v_cndmask_b32_e64 v150, v146, v150, s[10:11]
	v_cndmask_b32_e64 v151, v147, v151, s[10:11]
	v_cndmask_b32_e64 v152, v148, v152, s[10:11]
	v_cndmask_b32_e64 v153, v149, v153, s[10:11]
	v_cndmask_b32_e64 v142, v134, v142, s[10:11]
	v_cndmask_b32_e64 v143, v135, v143, s[10:11]
	v_cndmask_b32_e64 v144, v136, v144, s[10:11]
	v_cndmask_b32_e64 v145, v137, v145, s[10:11]
	v_fmac_f32_dpp v188, v150, v76 row_ror:2 row_mask:0xf bank_mask:0xf
	v_fmac_f32_dpp v189, v151, v77 row_ror:2 row_mask:0xf bank_mask:0xf
	v_fmac_f32_dpp v190, v152, v78 row_ror:2 row_mask:0xf bank_mask:0xf
	v_fmac_f32_dpp v191, v153, v79 row_ror:2 row_mask:0xf bank_mask:0xf
	v_fmac_f32_dpp v192, v142, v92 row_ror:2 row_mask:0xf bank_mask:0xf
	v_fmac_f32_dpp v193, v143, v93 row_ror:2 row_mask:0xf bank_mask:0xf
	v_fmac_f32_dpp v194, v144, v94 row_ror:2 row_mask:0xf bank_mask:0xf
	v_fmac_f32_dpp v195, v145, v95 row_ror:2 row_mask:0xf bank_mask:0xf
	v_cndmask_b32_e64 v150, v146, v150, s[8:9]
	v_cndmask_b32_e64 v151, v147, v151, s[8:9]
	v_cndmask_b32_e64 v152, v148, v152, s[8:9]
	v_cndmask_b32_e64 v153, v149, v153, s[8:9]
	v_cndmask_b32_e64 v142, v134, v142, s[8:9]
	v_cndmask_b32_e64 v143, v135, v143, s[8:9]
	v_cndmask_b32_e64 v144, v136, v144, s[8:9]
	v_cndmask_b32_e64 v145, v137, v145, s[8:9]
	v_fmac_f32_dpp v188, v150, v80 row_ror:1 row_mask:0xf bank_mask:0xf
	v_fmac_f32_dpp v189, v151, v81 row_ror:1 row_mask:0xf bank_mask:0xf
	v_fmac_f32_dpp v190, v152, v82 row_ror:1 row_mask:0xf bank_mask:0xf
	v_fmac_f32_dpp v191, v153, v83 row_ror:1 row_mask:0xf bank_mask:0xf
	v_fmac_f32_dpp v192, v142, v96 row_ror:1 row_mask:0xf bank_mask:0xf
	v_fmac_f32_dpp v193, v143, v97 row_ror:1 row_mask:0xf bank_mask:0xf
	v_fmac_f32_dpp v194, v144, v98 row_ror:1 row_mask:0xf bank_mask:0xf
	v_fmac_f32_dpp v195, v145, v99 row_ror:1 row_mask:0xf bank_mask:0xf
	v_pk_mul_f32 v[196:197], v[188:189], v[216:217] op_sel_hi:[1,0]
	v_pk_mul_f32 v[198:199], v[190:191], v[216:217] op_sel_hi:[1,0]
	v_exp_f32_e32 v196, v196
	v_exp_f32_e32 v197, v197
	v_exp_f32_e32 v198, v198
	v_exp_f32_e32 v199, v199
	v_pk_add_f32 v[196:197], v[196:197], v[214:215] op_sel_hi:[1,0]
	v_pk_add_f32 v[198:199], v[198:199], v[214:215] op_sel_hi:[1,0]
	v_rcp_f32_e32 v196, v196
	v_rcp_f32_e32 v197, v197
	v_rcp_f32_e32 v198, v198
	v_rcp_f32_e32 v199, v199
	v_pk_mul_f32 v[188:189], v[188:189], v[196:197]
	v_pk_mul_f32 v[190:191], v[190:191], v[198:199]
	v_pk_mul_f32 v[188:189], v[188:189], v[192:193]
	v_pk_mul_f32 v[190:191], v[190:191], v[194:195]
	v_cvt_pk_bf16_f32 v150, v188, v189
	v_cvt_pk_bf16_f32 v151, v190, v191
	v_add_u32_e32 v213, 0x2c000, v212
	global_load_dwordx4 v[142:145], v213, s[82:83] offset:16
	v_pk_fma_f32 v[188:189], v[138:139], v[84:85], v[88:89]
	v_pk_fma_f32 v[190:191], v[140:141], v[86:87], v[90:91]
	v_pk_fma_f32 v[192:193], v[130:131], v[100:101], v[104:105]
	v_pk_fma_f32 v[194:195], v[132:133], v[102:103], v[106:107]
	v_cndmask_b32_e64 v146, v138, v146, s[10:11]
	v_cndmask_b32_e64 v147, v139, v147, s[10:11]
	v_cndmask_b32_e64 v148, v140, v148, s[10:11]
	v_cndmask_b32_e64 v149, v141, v149, s[10:11]
	v_cndmask_b32_e64 v134, v130, v134, s[10:11]
	v_cndmask_b32_e64 v135, v131, v135, s[10:11]
	v_cndmask_b32_e64 v136, v132, v136, s[10:11]
	v_cndmask_b32_e64 v137, v133, v137, s[10:11]
	v_fmac_f32_dpp v188, v146, v76 row_ror:2 row_mask:0xf bank_mask:0xf
	v_fmac_f32_dpp v189, v147, v77 row_ror:2 row_mask:0xf bank_mask:0xf
	v_fmac_f32_dpp v190, v148, v78 row_ror:2 row_mask:0xf bank_mask:0xf
	v_fmac_f32_dpp v191, v149, v79 row_ror:2 row_mask:0xf bank_mask:0xf
	v_fmac_f32_dpp v192, v134, v92 row_ror:2 row_mask:0xf bank_mask:0xf
	v_fmac_f32_dpp v193, v135, v93 row_ror:2 row_mask:0xf bank_mask:0xf
	v_fmac_f32_dpp v194, v136, v94 row_ror:2 row_mask:0xf bank_mask:0xf
	v_fmac_f32_dpp v195, v137, v95 row_ror:2 row_mask:0xf bank_mask:0xf
	v_cndmask_b32_e64 v146, v138, v146, s[8:9]
	v_cndmask_b32_e64 v147, v139, v147, s[8:9]
	v_cndmask_b32_e64 v148, v140, v148, s[8:9]
	v_cndmask_b32_e64 v149, v141, v149, s[8:9]
	v_cndmask_b32_e64 v134, v130, v134, s[8:9]
	v_cndmask_b32_e64 v135, v131, v135, s[8:9]
	v_cndmask_b32_e64 v136, v132, v136, s[8:9]
	v_cndmask_b32_e64 v137, v133, v137, s[8:9]
	v_fmac_f32_dpp v188, v146, v80 row_ror:1 row_mask:0xf bank_mask:0xf
	v_fmac_f32_dpp v189, v147, v81 row_ror:1 row_mask:0xf bank_mask:0xf
	v_fmac_f32_dpp v190, v148, v82 row_ror:1 row_mask:0xf bank_mask:0xf
	v_fmac_f32_dpp v191, v149, v83 row_ror:1 row_mask:0xf bank_mask:0xf
	v_fmac_f32_dpp v192, v134, v96 row_ror:1 row_mask:0xf bank_mask:0xf
	v_fmac_f32_dpp v193, v135, v97 row_ror:1 row_mask:0xf bank_mask:0xf
	v_fmac_f32_dpp v194, v136, v98 row_ror:1 row_mask:0xf bank_mask:0xf
	v_fmac_f32_dpp v195, v137, v99 row_ror:1 row_mask:0xf bank_mask:0xf
	v_pk_mul_f32 v[196:197], v[188:189], v[216:217] op_sel_hi:[1,0]
	v_pk_mul_f32 v[198:199], v[190:191], v[216:217] op_sel_hi:[1,0]
	v_exp_f32_e32 v196, v196
	v_exp_f32_e32 v197, v197
	v_exp_f32_e32 v198, v198
	v_exp_f32_e32 v199, v199
	v_pk_add_f32 v[196:197], v[196:197], v[214:215] op_sel_hi:[1,0]
	v_pk_add_f32 v[198:199], v[198:199], v[214:215] op_sel_hi:[1,0]
	v_rcp_f32_e32 v196, v196
	v_rcp_f32_e32 v197, v197
	v_rcp_f32_e32 v198, v198
	v_rcp_f32_e32 v199, v199
	v_pk_mul_f32 v[188:189], v[188:189], v[196:197]
	v_pk_mul_f32 v[190:191], v[190:191], v[198:199]
	v_pk_mul_f32 v[188:189], v[188:189], v[192:193]
	v_pk_mul_f32 v[190:191], v[190:191], v[194:195]
	v_cvt_pk_bf16_f32 v146, v188, v189
	v_cvt_pk_bf16_f32 v147, v190, v191
	v_add_u32_e32 v213, 0x37000, v212
	global_load_dwordx4 v[134:137], v213, s[82:83] offset:16
	v_pk_fma_f32 v[188:189], v[126:127], v[84:85], v[88:89]
	v_pk_fma_f32 v[190:191], v[128:129], v[86:87], v[90:91]
	v_pk_fma_f32 v[192:193], v[118:119], v[100:101], v[104:105]
	v_pk_fma_f32 v[194:195], v[120:121], v[102:103], v[106:107]
	v_cndmask_b32_e64 v138, v126, v138, s[10:11]
	v_cndmask_b32_e64 v139, v127, v139, s[10:11]
	v_cndmask_b32_e64 v140, v128, v140, s[10:11]
	v_cndmask_b32_e64 v141, v129, v141, s[10:11]
	v_cndmask_b32_e64 v130, v118, v130, s[10:11]
	v_cndmask_b32_e64 v131, v119, v131, s[10:11]
	v_cndmask_b32_e64 v132, v120, v132, s[10:11]
	v_cndmask_b32_e64 v133, v121, v133, s[10:11]
	v_fmac_f32_dpp v188, v138, v76 row_ror:2 row_mask:0xf bank_mask:0xf
	v_fmac_f32_dpp v189, v139, v77 row_ror:2 row_mask:0xf bank_mask:0xf
	v_fmac_f32_dpp v190, v140, v78 row_ror:2 row_mask:0xf bank_mask:0xf
	v_fmac_f32_dpp v191, v141, v79 row_ror:2 row_mask:0xf bank_mask:0xf
	v_fmac_f32_dpp v192, v130, v92 row_ror:2 row_mask:0xf bank_mask:0xf
	v_fmac_f32_dpp v193, v131, v93 row_ror:2 row_mask:0xf bank_mask:0xf
	v_fmac_f32_dpp v194, v132, v94 row_ror:2 row_mask:0xf bank_mask:0xf
	v_fmac_f32_dpp v195, v133, v95 row_ror:2 row_mask:0xf bank_mask:0xf
	v_cndmask_b32_e64 v138, v126, v138, s[8:9]
	v_cndmask_b32_e64 v139, v127, v139, s[8:9]
	v_cndmask_b32_e64 v140, v128, v140, s[8:9]
	v_cndmask_b32_e64 v141, v129, v141, s[8:9]
	v_cndmask_b32_e64 v130, v118, v130, s[8:9]
	v_cndmask_b32_e64 v131, v119, v131, s[8:9]
	v_cndmask_b32_e64 v132, v120, v132, s[8:9]
	v_cndmask_b32_e64 v133, v121, v133, s[8:9]
	v_fmac_f32_dpp v188, v138, v80 row_ror:1 row_mask:0xf bank_mask:0xf
	v_fmac_f32_dpp v189, v139, v81 row_ror:1 row_mask:0xf bank_mask:0xf
	v_fmac_f32_dpp v190, v140, v82 row_ror:1 row_mask:0xf bank_mask:0xf
	v_fmac_f32_dpp v191, v141, v83 row_ror:1 row_mask:0xf bank_mask:0xf
	v_fmac_f32_dpp v192, v130, v96 row_ror:1 row_mask:0xf bank_mask:0xf
	v_fmac_f32_dpp v193, v131, v97 row_ror:1 row_mask:0xf bank_mask:0xf
	v_fmac_f32_dpp v194, v132, v98 row_ror:1 row_mask:0xf bank_mask:0xf
	v_fmac_f32_dpp v195, v133, v99 row_ror:1 row_mask:0xf bank_mask:0xf
	v_pk_mul_f32 v[196:197], v[188:189], v[216:217] op_sel_hi:[1,0]
	v_pk_mul_f32 v[198:199], v[190:191], v[216:217] op_sel_hi:[1,0]
	v_exp_f32_e32 v196, v196
	v_exp_f32_e32 v197, v197
	v_exp_f32_e32 v198, v198
	v_exp_f32_e32 v199, v199
	v_pk_add_f32 v[196:197], v[196:197], v[214:215] op_sel_hi:[1,0]
	v_pk_add_f32 v[198:199], v[198:199], v[214:215] op_sel_hi:[1,0]
	v_rcp_f32_e32 v196, v196
	v_rcp_f32_e32 v197, v197
	v_rcp_f32_e32 v198, v198
	v_rcp_f32_e32 v199, v199
	v_pk_mul_f32 v[188:189], v[188:189], v[196:197]
	v_pk_mul_f32 v[190:191], v[190:191], v[198:199]
	v_pk_mul_f32 v[188:189], v[188:189], v[192:193]
	v_pk_mul_f32 v[190:191], v[190:191], v[194:195]
	v_cvt_pk_bf16_f32 v138, v188, v189
	v_cvt_pk_bf16_f32 v139, v190, v191
	v_add_u32_e32 v213, 0xb000, v212
	global_load_dwordx4 v[130:133], v213, s[84:85] offset:16
	v_pk_fma_f32 v[188:189], v[122:123], v[84:85], v[88:89]
	v_pk_fma_f32 v[190:191], v[124:125], v[86:87], v[90:91]
	v_pk_fma_f32 v[192:193], v[110:111], v[100:101], v[104:105]
	v_pk_fma_f32 v[194:195], v[112:113], v[102:103], v[106:107]
	v_cndmask_b32_e64 v126, v122, v126, s[10:11]
	v_cndmask_b32_e64 v127, v123, v127, s[10:11]
	v_cndmask_b32_e64 v128, v124, v128, s[10:11]
	v_cndmask_b32_e64 v129, v125, v129, s[10:11]
	v_cndmask_b32_e64 v118, v110, v118, s[10:11]
	v_cndmask_b32_e64 v119, v111, v119, s[10:11]
	v_cndmask_b32_e64 v120, v112, v120, s[10:11]
	v_cndmask_b32_e64 v121, v113, v121, s[10:11]
	v_fmac_f32_dpp v188, v126, v76 row_ror:2 row_mask:0xf bank_mask:0xf
	v_fmac_f32_dpp v189, v127, v77 row_ror:2 row_mask:0xf bank_mask:0xf
	v_fmac_f32_dpp v190, v128, v78 row_ror:2 row_mask:0xf bank_mask:0xf
	v_fmac_f32_dpp v191, v129, v79 row_ror:2 row_mask:0xf bank_mask:0xf
	v_fmac_f32_dpp v192, v118, v92 row_ror:2 row_mask:0xf bank_mask:0xf
	v_fmac_f32_dpp v193, v119, v93 row_ror:2 row_mask:0xf bank_mask:0xf
	v_fmac_f32_dpp v194, v120, v94 row_ror:2 row_mask:0xf bank_mask:0xf
	v_fmac_f32_dpp v195, v121, v95 row_ror:2 row_mask:0xf bank_mask:0xf
	v_cndmask_b32_e64 v126, v122, v126, s[8:9]
	v_cndmask_b32_e64 v127, v123, v127, s[8:9]
	v_cndmask_b32_e64 v128, v124, v128, s[8:9]
	v_cndmask_b32_e64 v129, v125, v129, s[8:9]
	v_cndmask_b32_e64 v118, v110, v118, s[8:9]
	v_cndmask_b32_e64 v119, v111, v119, s[8:9]
	v_cndmask_b32_e64 v120, v112, v120, s[8:9]
	v_cndmask_b32_e64 v121, v113, v121, s[8:9]
	v_fmac_f32_dpp v188, v126, v80 row_ror:1 row_mask:0xf bank_mask:0xf
	v_fmac_f32_dpp v189, v127, v81 row_ror:1 row_mask:0xf bank_mask:0xf
	v_fmac_f32_dpp v190, v128, v82 row_ror:1 row_mask:0xf bank_mask:0xf
	v_fmac_f32_dpp v191, v129, v83 row_ror:1 row_mask:0xf bank_mask:0xf
	v_fmac_f32_dpp v192, v118, v96 row_ror:1 row_mask:0xf bank_mask:0xf
	v_fmac_f32_dpp v193, v119, v97 row_ror:1 row_mask:0xf bank_mask:0xf
	v_fmac_f32_dpp v194, v120, v98 row_ror:1 row_mask:0xf bank_mask:0xf
	v_fmac_f32_dpp v195, v121, v99 row_ror:1 row_mask:0xf bank_mask:0xf
	v_pk_mul_f32 v[196:197], v[188:189], v[216:217] op_sel_hi:[1,0]
	v_pk_mul_f32 v[198:199], v[190:191], v[216:217] op_sel_hi:[1,0]
	v_exp_f32_e32 v196, v196
	v_exp_f32_e32 v197, v197
	v_exp_f32_e32 v198, v198
	v_exp_f32_e32 v199, v199
	v_pk_add_f32 v[196:197], v[196:197], v[214:215] op_sel_hi:[1,0]
	v_pk_add_f32 v[198:199], v[198:199], v[214:215] op_sel_hi:[1,0]
	v_rcp_f32_e32 v196, v196
	v_rcp_f32_e32 v197, v197
	v_rcp_f32_e32 v198, v198
	v_rcp_f32_e32 v199, v199
	v_pk_mul_f32 v[188:189], v[188:189], v[196:197]
	v_pk_mul_f32 v[190:191], v[190:191], v[198:199]
	v_pk_mul_f32 v[188:189], v[188:189], v[192:193]
	v_pk_mul_f32 v[190:191], v[190:191], v[194:195]
	v_cvt_pk_bf16_f32 v126, v188, v189
	v_cvt_pk_bf16_f32 v127, v190, v191
	v_add_u32_e32 v213, 0x26800, v212
	global_load_dwordx4 v[118:121], v213, s[82:83] offset:16
	v_pk_fma_f32 v[188:189], v[114:115], v[84:85], v[88:89]
	v_pk_fma_f32 v[190:191], v[116:117], v[86:87], v[90:91]
	v_pk_fma_f32 v[192:193], v[68:69], v[100:101], v[104:105]
	v_pk_fma_f32 v[194:195], v[70:71], v[102:103], v[106:107]
	v_cndmask_b32_e64 v122, v114, v122, s[10:11]
	v_cndmask_b32_e64 v123, v115, v123, s[10:11]
	v_cndmask_b32_e64 v124, v116, v124, s[10:11]
	v_cndmask_b32_e64 v125, v117, v125, s[10:11]
	v_cndmask_b32_e64 v110, v68, v110, s[10:11]
	v_cndmask_b32_e64 v111, v69, v111, s[10:11]
	v_cndmask_b32_e64 v112, v70, v112, s[10:11]
	v_cndmask_b32_e64 v113, v71, v113, s[10:11]
	v_fmac_f32_dpp v188, v122, v76 row_ror:2 row_mask:0xf bank_mask:0xf
	v_fmac_f32_dpp v189, v123, v77 row_ror:2 row_mask:0xf bank_mask:0xf
	v_fmac_f32_dpp v190, v124, v78 row_ror:2 row_mask:0xf bank_mask:0xf
	v_fmac_f32_dpp v191, v125, v79 row_ror:2 row_mask:0xf bank_mask:0xf
	v_fmac_f32_dpp v192, v110, v92 row_ror:2 row_mask:0xf bank_mask:0xf
	v_fmac_f32_dpp v193, v111, v93 row_ror:2 row_mask:0xf bank_mask:0xf
	v_fmac_f32_dpp v194, v112, v94 row_ror:2 row_mask:0xf bank_mask:0xf
	v_fmac_f32_dpp v195, v113, v95 row_ror:2 row_mask:0xf bank_mask:0xf
	v_cndmask_b32_e64 v122, v114, v122, s[8:9]
	v_cndmask_b32_e64 v123, v115, v123, s[8:9]
	v_cndmask_b32_e64 v124, v116, v124, s[8:9]
	v_cndmask_b32_e64 v125, v117, v125, s[8:9]
	v_cndmask_b32_e64 v110, v68, v110, s[8:9]
	v_cndmask_b32_e64 v111, v69, v111, s[8:9]
	v_cndmask_b32_e64 v112, v70, v112, s[8:9]
	v_cndmask_b32_e64 v113, v71, v113, s[8:9]
	v_fmac_f32_dpp v188, v122, v80 row_ror:1 row_mask:0xf bank_mask:0xf
	v_fmac_f32_dpp v189, v123, v81 row_ror:1 row_mask:0xf bank_mask:0xf
	v_fmac_f32_dpp v190, v124, v82 row_ror:1 row_mask:0xf bank_mask:0xf
	v_fmac_f32_dpp v191, v125, v83 row_ror:1 row_mask:0xf bank_mask:0xf
	v_fmac_f32_dpp v192, v110, v96 row_ror:1 row_mask:0xf bank_mask:0xf
	v_fmac_f32_dpp v193, v111, v97 row_ror:1 row_mask:0xf bank_mask:0xf
	v_fmac_f32_dpp v194, v112, v98 row_ror:1 row_mask:0xf bank_mask:0xf
	v_fmac_f32_dpp v195, v113, v99 row_ror:1 row_mask:0xf bank_mask:0xf
	v_pk_mul_f32 v[196:197], v[188:189], v[216:217] op_sel_hi:[1,0]
	v_pk_mul_f32 v[198:199], v[190:191], v[216:217] op_sel_hi:[1,0]
	v_exp_f32_e32 v196, v196
	v_exp_f32_e32 v197, v197
	v_exp_f32_e32 v198, v198
	v_exp_f32_e32 v199, v199
	v_pk_add_f32 v[196:197], v[196:197], v[214:215] op_sel_hi:[1,0]
	v_pk_add_f32 v[198:199], v[198:199], v[214:215] op_sel_hi:[1,0]
	v_rcp_f32_e32 v196, v196
	v_rcp_f32_e32 v197, v197
	v_rcp_f32_e32 v198, v198
	v_rcp_f32_e32 v199, v199
	v_pk_mul_f32 v[188:189], v[188:189], v[196:197]
	v_pk_mul_f32 v[190:191], v[190:191], v[198:199]
	v_pk_mul_f32 v[188:189], v[188:189], v[192:193]
	v_pk_mul_f32 v[190:191], v[190:191], v[194:195]
	v_cvt_pk_bf16_f32 v122, v188, v189
	v_cvt_pk_bf16_f32 v123, v190, v191
	v_add_u32_e32 v213, 0x31800, v212
	global_load_dwordx4 v[110:113], v213, s[82:83] offset:16
	v_pk_fma_f32 v[188:189], v[72:73], v[84:85], v[88:89]
	v_pk_fma_f32 v[190:191], v[74:75], v[86:87], v[90:91]
	v_pk_fma_f32 v[192:193], v[64:65], v[100:101], v[104:105]
	v_pk_fma_f32 v[194:195], v[66:67], v[102:103], v[106:107]
	v_cndmask_b32_e64 v114, v72, v114, s[10:11]
	v_cndmask_b32_e64 v115, v73, v115, s[10:11]
	v_cndmask_b32_e64 v116, v74, v116, s[10:11]
	v_cndmask_b32_e64 v117, v75, v117, s[10:11]
	v_cndmask_b32_e64 v68, v64, v68, s[10:11]
	v_cndmask_b32_e64 v69, v65, v69, s[10:11]
	v_cndmask_b32_e64 v70, v66, v70, s[10:11]
	v_cndmask_b32_e64 v71, v67, v71, s[10:11]
	v_fmac_f32_dpp v188, v114, v76 row_ror:2 row_mask:0xf bank_mask:0xf
	v_fmac_f32_dpp v189, v115, v77 row_ror:2 row_mask:0xf bank_mask:0xf
	v_fmac_f32_dpp v190, v116, v78 row_ror:2 row_mask:0xf bank_mask:0xf
	v_fmac_f32_dpp v191, v117, v79 row_ror:2 row_mask:0xf bank_mask:0xf
	v_fmac_f32_dpp v192, v68, v92 row_ror:2 row_mask:0xf bank_mask:0xf
	v_fmac_f32_dpp v193, v69, v93 row_ror:2 row_mask:0xf bank_mask:0xf
	v_fmac_f32_dpp v194, v70, v94 row_ror:2 row_mask:0xf bank_mask:0xf
	v_fmac_f32_dpp v195, v71, v95 row_ror:2 row_mask:0xf bank_mask:0xf
	v_cndmask_b32_e64 v114, v72, v114, s[8:9]
	v_cndmask_b32_e64 v115, v73, v115, s[8:9]
	v_cndmask_b32_e64 v116, v74, v116, s[8:9]
	v_cndmask_b32_e64 v117, v75, v117, s[8:9]
	v_cndmask_b32_e64 v68, v64, v68, s[8:9]
	v_cndmask_b32_e64 v69, v65, v69, s[8:9]
	v_cndmask_b32_e64 v70, v66, v70, s[8:9]
	v_cndmask_b32_e64 v71, v67, v71, s[8:9]
	v_fmac_f32_dpp v188, v114, v80 row_ror:1 row_mask:0xf bank_mask:0xf
	v_fmac_f32_dpp v189, v115, v81 row_ror:1 row_mask:0xf bank_mask:0xf
	v_fmac_f32_dpp v190, v116, v82 row_ror:1 row_mask:0xf bank_mask:0xf
	v_fmac_f32_dpp v191, v117, v83 row_ror:1 row_mask:0xf bank_mask:0xf
	v_fmac_f32_dpp v192, v68, v96 row_ror:1 row_mask:0xf bank_mask:0xf
	v_fmac_f32_dpp v193, v69, v97 row_ror:1 row_mask:0xf bank_mask:0xf
	v_fmac_f32_dpp v194, v70, v98 row_ror:1 row_mask:0xf bank_mask:0xf
	v_fmac_f32_dpp v195, v71, v99 row_ror:1 row_mask:0xf bank_mask:0xf
	v_pk_mul_f32 v[196:197], v[188:189], v[216:217] op_sel_hi:[1,0]
	v_pk_mul_f32 v[198:199], v[190:191], v[216:217] op_sel_hi:[1,0]
	v_exp_f32_e32 v196, v196
	v_exp_f32_e32 v197, v197
	v_exp_f32_e32 v198, v198
	v_exp_f32_e32 v199, v199
	v_pk_add_f32 v[196:197], v[196:197], v[214:215] op_sel_hi:[1,0]
	v_pk_add_f32 v[198:199], v[198:199], v[214:215] op_sel_hi:[1,0]
	v_rcp_f32_e32 v196, v196
	v_rcp_f32_e32 v197, v197
	v_rcp_f32_e32 v198, v198
	v_rcp_f32_e32 v199, v199
	v_pk_mul_f32 v[188:189], v[188:189], v[196:197]
	v_pk_mul_f32 v[190:191], v[190:191], v[198:199]
	v_pk_mul_f32 v[188:189], v[188:189], v[192:193]
	v_pk_mul_f32 v[190:191], v[190:191], v[194:195]
	v_cvt_pk_bf16_f32 v114, v188, v189
	v_cvt_pk_bf16_f32 v115, v190, v191
	s_waitcnt vmcnt(0)
	v_pk_fma_f32 v[188:189], v[60:61], v[134:135], v[130:131]
	v_pk_fma_f32 v[190:191], v[62:63], v[136:137], v[132:133]
	v_pk_fma_f32 v[192:193], v[56:57], v[204:205], v[208:209]
	v_pk_fma_f32 v[194:195], v[58:59], v[206:207], v[210:211]
	v_fmac_f32_dpp v188, v60, v142 row_shr:1 row_mask:0xf bank_mask:0xf
	v_fmac_f32_dpp v189, v61, v143 row_shr:1 row_mask:0xf bank_mask:0xf
	v_fmac_f32_dpp v190, v62, v144 row_shr:1 row_mask:0xf bank_mask:0xf
	v_fmac_f32_dpp v191, v63, v145 row_shr:1 row_mask:0xf bank_mask:0xf
	v_fmac_f32_dpp v192, v56, v110 row_shr:1 row_mask:0xf bank_mask:0xf
	v_fmac_f32_dpp v193, v57, v111 row_shr:1 row_mask:0xf bank_mask:0xf
	v_fmac_f32_dpp v194, v58, v112 row_shr:1 row_mask:0xf bank_mask:0xf
	v_fmac_f32_dpp v195, v59, v113 row_shr:1 row_mask:0xf bank_mask:0xf
	v_fmac_f32_dpp v188, v60, v154 row_shr:2 row_mask:0xf bank_mask:0xf
	v_fmac_f32_dpp v189, v61, v155 row_shr:2 row_mask:0xf bank_mask:0xf
	v_fmac_f32_dpp v190, v62, v156 row_shr:2 row_mask:0xf bank_mask:0xf
	v_fmac_f32_dpp v191, v63, v157 row_shr:2 row_mask:0xf bank_mask:0xf
	v_fmac_f32_dpp v192, v56, v118 row_shr:2 row_mask:0xf bank_mask:0xf
	v_fmac_f32_dpp v193, v57, v119 row_shr:2 row_mask:0xf bank_mask:0xf
	v_fmac_f32_dpp v194, v58, v120 row_shr:2 row_mask:0xf bank_mask:0xf
	v_fmac_f32_dpp v195, v59, v121 row_shr:2 row_mask:0xf bank_mask:0xf
	v_pk_mul_f32 v[196:197], v[188:189], v[216:217] op_sel_hi:[1,0]
	v_pk_mul_f32 v[198:199], v[190:191], v[216:217] op_sel_hi:[1,0]
	v_exp_f32_e32 v196, v196
	v_exp_f32_e32 v197, v197
	v_exp_f32_e32 v198, v198
	v_exp_f32_e32 v199, v199
	v_pk_add_f32 v[196:197], v[196:197], v[214:215] op_sel_hi:[1,0]
	v_pk_add_f32 v[198:199], v[198:199], v[214:215] op_sel_hi:[1,0]
	v_rcp_f32_e32 v196, v196
	v_rcp_f32_e32 v197, v197
	v_rcp_f32_e32 v198, v198
	v_rcp_f32_e32 v199, v199
	v_pk_mul_f32 v[188:189], v[188:189], v[196:197]
	v_pk_mul_f32 v[190:191], v[190:191], v[198:199]
	v_pk_mul_f32 v[188:189], v[188:189], v[192:193]
	v_pk_mul_f32 v[190:191], v[190:191], v[194:195]
	v_cvt_pk_bf16_f32 v202, v188, v189
	v_cvt_pk_bf16_f32 v203, v190, v191
	s_mov_b64 exec, vcc
	global_store_dwordx4 v215, v[200:203], s[96:97] nt
	s_mov_b64 exec, -1
	v_pk_fma_f32 v[188:189], v[52:53], v[134:135], v[130:131]
	v_pk_fma_f32 v[190:191], v[54:55], v[136:137], v[132:133]
	v_pk_fma_f32 v[192:193], v[44:45], v[204:205], v[208:209]
	v_pk_fma_f32 v[194:195], v[46:47], v[206:207], v[210:211]
	v_cndmask_b32_e64 v60, v52, v60, s[10:11]
	v_cndmask_b32_e64 v61, v53, v61, s[10:11]
	v_cndmask_b32_e64 v62, v54, v62, s[10:11]
	v_cndmask_b32_e64 v63, v55, v63, s[10:11]
	v_cndmask_b32_e64 v56, v44, v56, s[10:11]
	v_cndmask_b32_e64 v57, v45, v57, s[10:11]
	v_cndmask_b32_e64 v58, v46, v58, s[10:11]
	v_cndmask_b32_e64 v59, v47, v59, s[10:11]
	v_fmac_f32_dpp v188, v60, v154 row_ror:2 row_mask:0xf bank_mask:0xf
	v_fmac_f32_dpp v189, v61, v155 row_ror:2 row_mask:0xf bank_mask:0xf
	v_fmac_f32_dpp v190, v62, v156 row_ror:2 row_mask:0xf bank_mask:0xf
	v_fmac_f32_dpp v191, v63, v157 row_ror:2 row_mask:0xf bank_mask:0xf
	v_fmac_f32_dpp v192, v56, v118 row_ror:2 row_mask:0xf bank_mask:0xf
	v_fmac_f32_dpp v193, v57, v119 row_ror:2 row_mask:0xf bank_mask:0xf
	v_fmac_f32_dpp v194, v58, v120 row_ror:2 row_mask:0xf bank_mask:0xf
	v_fmac_f32_dpp v195, v59, v121 row_ror:2 row_mask:0xf bank_mask:0xf
	v_cndmask_b32_e64 v60, v52, v60, s[8:9]
	v_cndmask_b32_e64 v61, v53, v61, s[8:9]
	v_cndmask_b32_e64 v62, v54, v62, s[8:9]
	v_cndmask_b32_e64 v63, v55, v63, s[8:9]
	v_cndmask_b32_e64 v56, v44, v56, s[8:9]
	v_cndmask_b32_e64 v57, v45, v57, s[8:9]
	v_cndmask_b32_e64 v58, v46, v58, s[8:9]
	v_cndmask_b32_e64 v59, v47, v59, s[8:9]
	v_fmac_f32_dpp v188, v60, v142 row_ror:1 row_mask:0xf bank_mask:0xf
	v_fmac_f32_dpp v189, v61, v143 row_ror:1 row_mask:0xf bank_mask:0xf
	v_fmac_f32_dpp v190, v62, v144 row_ror:1 row_mask:0xf bank_mask:0xf
	v_fmac_f32_dpp v191, v63, v145 row_ror:1 row_mask:0xf bank_mask:0xf
	v_fmac_f32_dpp v192, v56, v110 row_ror:1 row_mask:0xf bank_mask:0xf
	v_fmac_f32_dpp v193, v57, v111 row_ror:1 row_mask:0xf bank_mask:0xf
	v_fmac_f32_dpp v194, v58, v112 row_ror:1 row_mask:0xf bank_mask:0xf
	v_fmac_f32_dpp v195, v59, v113 row_ror:1 row_mask:0xf bank_mask:0xf
	v_pk_mul_f32 v[196:197], v[188:189], v[216:217] op_sel_hi:[1,0]
	v_pk_mul_f32 v[198:199], v[190:191], v[216:217] op_sel_hi:[1,0]
	v_exp_f32_e32 v196, v196
	v_exp_f32_e32 v197, v197
	v_exp_f32_e32 v198, v198
	v_exp_f32_e32 v199, v199
	v_pk_add_f32 v[196:197], v[196:197], v[214:215] op_sel_hi:[1,0]
	v_pk_add_f32 v[198:199], v[198:199], v[214:215] op_sel_hi:[1,0]
	v_rcp_f32_e32 v196, v196
	v_rcp_f32_e32 v197, v197
	v_rcp_f32_e32 v198, v198
	v_rcp_f32_e32 v199, v199
	v_pk_mul_f32 v[188:189], v[188:189], v[196:197]
	v_pk_mul_f32 v[190:191], v[190:191], v[198:199]
	v_pk_mul_f32 v[188:189], v[188:189], v[192:193]
	v_pk_mul_f32 v[190:191], v[190:191], v[194:195]
	v_cvt_pk_bf16_f32 v160, v188, v189
	v_cvt_pk_bf16_f32 v161, v190, v191
	v_add_u32_e32 v213, 0x2c000, v215
	global_store_dwordx4 v213, v[158:161], s[96:97] nt
	v_pk_fma_f32 v[188:189], v[48:49], v[134:135], v[130:131]
	v_pk_fma_f32 v[190:191], v[50:51], v[136:137], v[132:133]
	v_pk_fma_f32 v[192:193], v[36:37], v[204:205], v[208:209]
	v_pk_fma_f32 v[194:195], v[38:39], v[206:207], v[210:211]
	v_cndmask_b32_e64 v52, v48, v52, s[10:11]
	v_cndmask_b32_e64 v53, v49, v53, s[10:11]
	v_cndmask_b32_e64 v54, v50, v54, s[10:11]
	v_cndmask_b32_e64 v55, v51, v55, s[10:11]
	v_cndmask_b32_e64 v44, v36, v44, s[10:11]
	v_cndmask_b32_e64 v45, v37, v45, s[10:11]
	v_cndmask_b32_e64 v46, v38, v46, s[10:11]
	v_cndmask_b32_e64 v47, v39, v47, s[10:11]
	v_fmac_f32_dpp v188, v52, v154 row_ror:2 row_mask:0xf bank_mask:0xf
	v_fmac_f32_dpp v189, v53, v155 row_ror:2 row_mask:0xf bank_mask:0xf
	v_fmac_f32_dpp v190, v54, v156 row_ror:2 row_mask:0xf bank_mask:0xf
	v_fmac_f32_dpp v191, v55, v157 row_ror:2 row_mask:0xf bank_mask:0xf
	v_fmac_f32_dpp v192, v44, v118 row_ror:2 row_mask:0xf bank_mask:0xf
	v_fmac_f32_dpp v193, v45, v119 row_ror:2 row_mask:0xf bank_mask:0xf
	v_fmac_f32_dpp v194, v46, v120 row_ror:2 row_mask:0xf bank_mask:0xf
	v_fmac_f32_dpp v195, v47, v121 row_ror:2 row_mask:0xf bank_mask:0xf
	v_cndmask_b32_e64 v52, v48, v52, s[8:9]
	v_cndmask_b32_e64 v53, v49, v53, s[8:9]
	v_cndmask_b32_e64 v54, v50, v54, s[8:9]
	v_cndmask_b32_e64 v55, v51, v55, s[8:9]
	v_cndmask_b32_e64 v44, v36, v44, s[8:9]
	v_cndmask_b32_e64 v45, v37, v45, s[8:9]
	v_cndmask_b32_e64 v46, v38, v46, s[8:9]
	v_cndmask_b32_e64 v47, v39, v47, s[8:9]
	v_fmac_f32_dpp v188, v52, v142 row_ror:1 row_mask:0xf bank_mask:0xf
	v_fmac_f32_dpp v189, v53, v143 row_ror:1 row_mask:0xf bank_mask:0xf
	v_fmac_f32_dpp v190, v54, v144 row_ror:1 row_mask:0xf bank_mask:0xf
	v_fmac_f32_dpp v191, v55, v145 row_ror:1 row_mask:0xf bank_mask:0xf
	v_fmac_f32_dpp v192, v44, v110 row_ror:1 row_mask:0xf bank_mask:0xf
	v_fmac_f32_dpp v193, v45, v111 row_ror:1 row_mask:0xf bank_mask:0xf
	v_fmac_f32_dpp v194, v46, v112 row_ror:1 row_mask:0xf bank_mask:0xf
	v_fmac_f32_dpp v195, v47, v113 row_ror:1 row_mask:0xf bank_mask:0xf
	v_pk_mul_f32 v[196:197], v[188:189], v[216:217] op_sel_hi:[1,0]
	v_pk_mul_f32 v[198:199], v[190:191], v[216:217] op_sel_hi:[1,0]
	v_exp_f32_e32 v196, v196
	v_exp_f32_e32 v197, v197
	v_exp_f32_e32 v198, v198
	v_exp_f32_e32 v199, v199
	v_pk_add_f32 v[196:197], v[196:197], v[214:215] op_sel_hi:[1,0]
	v_pk_add_f32 v[198:199], v[198:199], v[214:215] op_sel_hi:[1,0]
	v_rcp_f32_e32 v196, v196
	v_rcp_f32_e32 v197, v197
	v_rcp_f32_e32 v198, v198
	v_rcp_f32_e32 v199, v199
	v_pk_mul_f32 v[188:189], v[188:189], v[196:197]
	v_pk_mul_f32 v[190:191], v[190:191], v[198:199]
	v_pk_mul_f32 v[188:189], v[188:189], v[192:193]
	v_pk_mul_f32 v[190:191], v[190:191], v[194:195]
	v_cvt_pk_bf16_f32 v152, v188, v189
	v_cvt_pk_bf16_f32 v153, v190, v191
	v_add_u32_e32 v213, 0x58000, v215
	global_store_dwordx4 v213, v[150:153], s[96:97] nt
	v_pk_fma_f32 v[188:189], v[40:41], v[134:135], v[130:131]
	v_pk_fma_f32 v[190:191], v[42:43], v[136:137], v[132:133]
	v_pk_fma_f32 v[192:193], v[32:33], v[204:205], v[208:209]
	v_pk_fma_f32 v[194:195], v[34:35], v[206:207], v[210:211]
	v_cndmask_b32_e64 v48, v40, v48, s[10:11]
	v_cndmask_b32_e64 v49, v41, v49, s[10:11]
	v_cndmask_b32_e64 v50, v42, v50, s[10:11]
	v_cndmask_b32_e64 v51, v43, v51, s[10:11]
	v_cndmask_b32_e64 v36, v32, v36, s[10:11]
	v_cndmask_b32_e64 v37, v33, v37, s[10:11]
	v_cndmask_b32_e64 v38, v34, v38, s[10:11]
	v_cndmask_b32_e64 v39, v35, v39, s[10:11]
	v_fmac_f32_dpp v188, v48, v154 row_ror:2 row_mask:0xf bank_mask:0xf
	v_fmac_f32_dpp v189, v49, v155 row_ror:2 row_mask:0xf bank_mask:0xf
	v_fmac_f32_dpp v190, v50, v156 row_ror:2 row_mask:0xf bank_mask:0xf
	v_fmac_f32_dpp v191, v51, v157 row_ror:2 row_mask:0xf bank_mask:0xf
	v_fmac_f32_dpp v192, v36, v118 row_ror:2 row_mask:0xf bank_mask:0xf
	v_fmac_f32_dpp v193, v37, v119 row_ror:2 row_mask:0xf bank_mask:0xf
	v_fmac_f32_dpp v194, v38, v120 row_ror:2 row_mask:0xf bank_mask:0xf
	v_fmac_f32_dpp v195, v39, v121 row_ror:2 row_mask:0xf bank_mask:0xf
	v_cndmask_b32_e64 v48, v40, v48, s[8:9]
	v_cndmask_b32_e64 v49, v41, v49, s[8:9]
	v_cndmask_b32_e64 v50, v42, v50, s[8:9]
	v_cndmask_b32_e64 v51, v43, v51, s[8:9]
	v_cndmask_b32_e64 v36, v32, v36, s[8:9]
	v_cndmask_b32_e64 v37, v33, v37, s[8:9]
	v_cndmask_b32_e64 v38, v34, v38, s[8:9]
	v_cndmask_b32_e64 v39, v35, v39, s[8:9]
	v_fmac_f32_dpp v188, v48, v142 row_ror:1 row_mask:0xf bank_mask:0xf
	v_fmac_f32_dpp v189, v49, v143 row_ror:1 row_mask:0xf bank_mask:0xf
	v_fmac_f32_dpp v190, v50, v144 row_ror:1 row_mask:0xf bank_mask:0xf
	v_fmac_f32_dpp v191, v51, v145 row_ror:1 row_mask:0xf bank_mask:0xf
	v_fmac_f32_dpp v192, v36, v110 row_ror:1 row_mask:0xf bank_mask:0xf
	v_fmac_f32_dpp v193, v37, v111 row_ror:1 row_mask:0xf bank_mask:0xf
	v_fmac_f32_dpp v194, v38, v112 row_ror:1 row_mask:0xf bank_mask:0xf
	v_fmac_f32_dpp v195, v39, v113 row_ror:1 row_mask:0xf bank_mask:0xf
	v_pk_mul_f32 v[196:197], v[188:189], v[216:217] op_sel_hi:[1,0]
	v_pk_mul_f32 v[198:199], v[190:191], v[216:217] op_sel_hi:[1,0]
	v_exp_f32_e32 v196, v196
	v_exp_f32_e32 v197, v197
	v_exp_f32_e32 v198, v198
	v_exp_f32_e32 v199, v199
	v_pk_add_f32 v[196:197], v[196:197], v[214:215] op_sel_hi:[1,0]
	v_pk_add_f32 v[198:199], v[198:199], v[214:215] op_sel_hi:[1,0]
	v_rcp_f32_e32 v196, v196
	v_rcp_f32_e32 v197, v197
	v_rcp_f32_e32 v198, v198
	v_rcp_f32_e32 v199, v199
	v_pk_mul_f32 v[188:189], v[188:189], v[196:197]
	v_pk_mul_f32 v[190:191], v[190:191], v[198:199]
	v_pk_mul_f32 v[188:189], v[188:189], v[192:193]
	v_pk_mul_f32 v[190:191], v[190:191], v[194:195]
	v_cvt_pk_bf16_f32 v148, v188, v189
	v_cvt_pk_bf16_f32 v149, v190, v191
	v_add_u32_e32 v213, 0x84000, v215
	global_store_dwordx4 v213, v[146:149], s[96:97] nt
	v_pk_fma_f32 v[188:189], v[28:29], v[134:135], v[130:131]
	v_pk_fma_f32 v[190:191], v[30:31], v[136:137], v[132:133]
	v_pk_fma_f32 v[192:193], v[16:17], v[204:205], v[208:209]
	v_pk_fma_f32 v[194:195], v[18:19], v[206:207], v[210:211]
	v_cndmask_b32_e64 v40, v28, v40, s[10:11]
	v_cndmask_b32_e64 v41, v29, v41, s[10:11]
	v_cndmask_b32_e64 v42, v30, v42, s[10:11]
	v_cndmask_b32_e64 v43, v31, v43, s[10:11]
	v_cndmask_b32_e64 v32, v16, v32, s[10:11]
	v_cndmask_b32_e64 v33, v17, v33, s[10:11]
	v_cndmask_b32_e64 v34, v18, v34, s[10:11]
	v_cndmask_b32_e64 v35, v19, v35, s[10:11]
	v_fmac_f32_dpp v188, v40, v154 row_ror:2 row_mask:0xf bank_mask:0xf
	v_fmac_f32_dpp v189, v41, v155 row_ror:2 row_mask:0xf bank_mask:0xf
	v_fmac_f32_dpp v190, v42, v156 row_ror:2 row_mask:0xf bank_mask:0xf
	v_fmac_f32_dpp v191, v43, v157 row_ror:2 row_mask:0xf bank_mask:0xf
	v_fmac_f32_dpp v192, v32, v118 row_ror:2 row_mask:0xf bank_mask:0xf
	v_fmac_f32_dpp v193, v33, v119 row_ror:2 row_mask:0xf bank_mask:0xf
	v_fmac_f32_dpp v194, v34, v120 row_ror:2 row_mask:0xf bank_mask:0xf
	v_fmac_f32_dpp v195, v35, v121 row_ror:2 row_mask:0xf bank_mask:0xf
	v_cndmask_b32_e64 v40, v28, v40, s[8:9]
	v_cndmask_b32_e64 v41, v29, v41, s[8:9]
	v_cndmask_b32_e64 v42, v30, v42, s[8:9]
	v_cndmask_b32_e64 v43, v31, v43, s[8:9]
	v_cndmask_b32_e64 v32, v16, v32, s[8:9]
	v_cndmask_b32_e64 v33, v17, v33, s[8:9]
	v_cndmask_b32_e64 v34, v18, v34, s[8:9]
	v_cndmask_b32_e64 v35, v19, v35, s[8:9]
	v_fmac_f32_dpp v188, v40, v142 row_ror:1 row_mask:0xf bank_mask:0xf
	v_fmac_f32_dpp v189, v41, v143 row_ror:1 row_mask:0xf bank_mask:0xf
	v_fmac_f32_dpp v190, v42, v144 row_ror:1 row_mask:0xf bank_mask:0xf
	v_fmac_f32_dpp v191, v43, v145 row_ror:1 row_mask:0xf bank_mask:0xf
	v_fmac_f32_dpp v192, v32, v110 row_ror:1 row_mask:0xf bank_mask:0xf
	v_fmac_f32_dpp v193, v33, v111 row_ror:1 row_mask:0xf bank_mask:0xf
	v_fmac_f32_dpp v194, v34, v112 row_ror:1 row_mask:0xf bank_mask:0xf
	v_fmac_f32_dpp v195, v35, v113 row_ror:1 row_mask:0xf bank_mask:0xf
	v_pk_mul_f32 v[196:197], v[188:189], v[216:217] op_sel_hi:[1,0]
	v_pk_mul_f32 v[198:199], v[190:191], v[216:217] op_sel_hi:[1,0]
	v_exp_f32_e32 v196, v196
	v_exp_f32_e32 v197, v197
	v_exp_f32_e32 v198, v198
	v_exp_f32_e32 v199, v199
	v_pk_add_f32 v[196:197], v[196:197], v[214:215] op_sel_hi:[1,0]
	v_pk_add_f32 v[198:199], v[198:199], v[214:215] op_sel_hi:[1,0]
	v_rcp_f32_e32 v196, v196
	v_rcp_f32_e32 v197, v197
	v_rcp_f32_e32 v198, v198
	v_rcp_f32_e32 v199, v199
	v_pk_mul_f32 v[188:189], v[188:189], v[196:197]
	v_pk_mul_f32 v[190:191], v[190:191], v[198:199]
	v_pk_mul_f32 v[188:189], v[188:189], v[192:193]
	v_pk_mul_f32 v[190:191], v[190:191], v[194:195]
	v_cvt_pk_bf16_f32 v140, v188, v189
	v_cvt_pk_bf16_f32 v141, v190, v191
	v_add_u32_e32 v213, 0xb0000, v215
	global_store_dwordx4 v213, v[138:141], s[96:97] nt
	v_pk_fma_f32 v[188:189], v[24:25], v[134:135], v[130:131]
	v_pk_fma_f32 v[190:191], v[26:27], v[136:137], v[132:133]
	v_pk_fma_f32 v[192:193], v[12:13], v[204:205], v[208:209]
	v_pk_fma_f32 v[194:195], v[14:15], v[206:207], v[210:211]
	v_cndmask_b32_e64 v28, v24, v28, s[10:11]
	v_cndmask_b32_e64 v29, v25, v29, s[10:11]
	v_cndmask_b32_e64 v30, v26, v30, s[10:11]
	v_cndmask_b32_e64 v31, v27, v31, s[10:11]
	v_cndmask_b32_e64 v16, v12, v16, s[10:11]
	v_cndmask_b32_e64 v17, v13, v17, s[10:11]
	v_cndmask_b32_e64 v18, v14, v18, s[10:11]
	v_cndmask_b32_e64 v19, v15, v19, s[10:11]
	v_fmac_f32_dpp v188, v28, v154 row_ror:2 row_mask:0xf bank_mask:0xf
	v_fmac_f32_dpp v189, v29, v155 row_ror:2 row_mask:0xf bank_mask:0xf
	v_fmac_f32_dpp v190, v30, v156 row_ror:2 row_mask:0xf bank_mask:0xf
	v_fmac_f32_dpp v191, v31, v157 row_ror:2 row_mask:0xf bank_mask:0xf
	v_fmac_f32_dpp v192, v16, v118 row_ror:2 row_mask:0xf bank_mask:0xf
	v_fmac_f32_dpp v193, v17, v119 row_ror:2 row_mask:0xf bank_mask:0xf
	v_fmac_f32_dpp v194, v18, v120 row_ror:2 row_mask:0xf bank_mask:0xf
	v_fmac_f32_dpp v195, v19, v121 row_ror:2 row_mask:0xf bank_mask:0xf
	v_cndmask_b32_e64 v28, v24, v28, s[8:9]
	v_cndmask_b32_e64 v29, v25, v29, s[8:9]
	v_cndmask_b32_e64 v30, v26, v30, s[8:9]
	v_cndmask_b32_e64 v31, v27, v31, s[8:9]
	v_cndmask_b32_e64 v16, v12, v16, s[8:9]
	v_cndmask_b32_e64 v17, v13, v17, s[8:9]
	v_cndmask_b32_e64 v18, v14, v18, s[8:9]
	v_cndmask_b32_e64 v19, v15, v19, s[8:9]
	v_fmac_f32_dpp v188, v28, v142 row_ror:1 row_mask:0xf bank_mask:0xf
	v_fmac_f32_dpp v189, v29, v143 row_ror:1 row_mask:0xf bank_mask:0xf
	v_fmac_f32_dpp v190, v30, v144 row_ror:1 row_mask:0xf bank_mask:0xf
	v_fmac_f32_dpp v191, v31, v145 row_ror:1 row_mask:0xf bank_mask:0xf
	v_fmac_f32_dpp v192, v16, v110 row_ror:1 row_mask:0xf bank_mask:0xf
	v_fmac_f32_dpp v193, v17, v111 row_ror:1 row_mask:0xf bank_mask:0xf
	v_fmac_f32_dpp v194, v18, v112 row_ror:1 row_mask:0xf bank_mask:0xf
	v_fmac_f32_dpp v195, v19, v113 row_ror:1 row_mask:0xf bank_mask:0xf
	v_pk_mul_f32 v[196:197], v[188:189], v[216:217] op_sel_hi:[1,0]
	v_pk_mul_f32 v[198:199], v[190:191], v[216:217] op_sel_hi:[1,0]
	v_exp_f32_e32 v196, v196
	v_exp_f32_e32 v197, v197
	v_exp_f32_e32 v198, v198
	v_exp_f32_e32 v199, v199
	v_pk_add_f32 v[196:197], v[196:197], v[214:215] op_sel_hi:[1,0]
	v_pk_add_f32 v[198:199], v[198:199], v[214:215] op_sel_hi:[1,0]
	v_rcp_f32_e32 v196, v196
	v_rcp_f32_e32 v197, v197
	v_rcp_f32_e32 v198, v198
	v_rcp_f32_e32 v199, v199
	v_pk_mul_f32 v[188:189], v[188:189], v[196:197]
	v_pk_mul_f32 v[190:191], v[190:191], v[198:199]
	v_pk_mul_f32 v[188:189], v[188:189], v[192:193]
	v_pk_mul_f32 v[190:191], v[190:191], v[194:195]
	v_cvt_pk_bf16_f32 v128, v188, v189
	v_cvt_pk_bf16_f32 v129, v190, v191
	v_add_u32_e32 v213, 0xdc000, v215
	global_store_dwordx4 v213, v[126:129], s[96:97] nt
	v_pk_fma_f32 v[188:189], v[20:21], v[134:135], v[130:131]
	v_pk_fma_f32 v[190:191], v[22:23], v[136:137], v[132:133]
	v_pk_fma_f32 v[192:193], v[8:9], v[204:205], v[208:209]
	v_pk_fma_f32 v[194:195], v[10:11], v[206:207], v[210:211]
	v_cndmask_b32_e64 v24, v20, v24, s[10:11]
	v_cndmask_b32_e64 v25, v21, v25, s[10:11]
	v_cndmask_b32_e64 v26, v22, v26, s[10:11]
	v_cndmask_b32_e64 v27, v23, v27, s[10:11]
	v_cndmask_b32_e64 v12, v8, v12, s[10:11]
	v_cndmask_b32_e64 v13, v9, v13, s[10:11]
	v_cndmask_b32_e64 v14, v10, v14, s[10:11]
	v_cndmask_b32_e64 v15, v11, v15, s[10:11]
	v_fmac_f32_dpp v188, v24, v154 row_ror:2 row_mask:0xf bank_mask:0xf
	v_fmac_f32_dpp v189, v25, v155 row_ror:2 row_mask:0xf bank_mask:0xf
	v_fmac_f32_dpp v190, v26, v156 row_ror:2 row_mask:0xf bank_mask:0xf
	v_fmac_f32_dpp v191, v27, v157 row_ror:2 row_mask:0xf bank_mask:0xf
	v_fmac_f32_dpp v192, v12, v118 row_ror:2 row_mask:0xf bank_mask:0xf
	v_fmac_f32_dpp v193, v13, v119 row_ror:2 row_mask:0xf bank_mask:0xf
	v_fmac_f32_dpp v194, v14, v120 row_ror:2 row_mask:0xf bank_mask:0xf
	v_fmac_f32_dpp v195, v15, v121 row_ror:2 row_mask:0xf bank_mask:0xf
	v_cndmask_b32_e64 v24, v20, v24, s[8:9]
	v_cndmask_b32_e64 v25, v21, v25, s[8:9]
	v_cndmask_b32_e64 v26, v22, v26, s[8:9]
	v_cndmask_b32_e64 v27, v23, v27, s[8:9]
	v_cndmask_b32_e64 v12, v8, v12, s[8:9]
	v_cndmask_b32_e64 v13, v9, v13, s[8:9]
	v_cndmask_b32_e64 v14, v10, v14, s[8:9]
	v_cndmask_b32_e64 v15, v11, v15, s[8:9]
	v_fmac_f32_dpp v188, v24, v142 row_ror:1 row_mask:0xf bank_mask:0xf
	v_fmac_f32_dpp v189, v25, v143 row_ror:1 row_mask:0xf bank_mask:0xf
	v_fmac_f32_dpp v190, v26, v144 row_ror:1 row_mask:0xf bank_mask:0xf
	v_fmac_f32_dpp v191, v27, v145 row_ror:1 row_mask:0xf bank_mask:0xf
	v_fmac_f32_dpp v192, v12, v110 row_ror:1 row_mask:0xf bank_mask:0xf
	v_fmac_f32_dpp v193, v13, v111 row_ror:1 row_mask:0xf bank_mask:0xf
	v_fmac_f32_dpp v194, v14, v112 row_ror:1 row_mask:0xf bank_mask:0xf
	v_fmac_f32_dpp v195, v15, v113 row_ror:1 row_mask:0xf bank_mask:0xf
	v_pk_mul_f32 v[196:197], v[188:189], v[216:217] op_sel_hi:[1,0]
	v_pk_mul_f32 v[198:199], v[190:191], v[216:217] op_sel_hi:[1,0]
	v_exp_f32_e32 v196, v196
	v_exp_f32_e32 v197, v197
	v_exp_f32_e32 v198, v198
	v_exp_f32_e32 v199, v199
	v_pk_add_f32 v[196:197], v[196:197], v[214:215] op_sel_hi:[1,0]
	v_pk_add_f32 v[198:199], v[198:199], v[214:215] op_sel_hi:[1,0]
	v_rcp_f32_e32 v196, v196
	v_rcp_f32_e32 v197, v197
	v_rcp_f32_e32 v198, v198
	v_rcp_f32_e32 v199, v199
	v_pk_mul_f32 v[188:189], v[188:189], v[196:197]
	v_pk_mul_f32 v[190:191], v[190:191], v[198:199]
	v_pk_mul_f32 v[188:189], v[188:189], v[192:193]
	v_pk_mul_f32 v[190:191], v[190:191], v[194:195]
	v_cvt_pk_bf16_f32 v124, v188, v189
	v_cvt_pk_bf16_f32 v125, v190, v191
	v_add_u32_e32 v213, 0x108000, v215
	global_store_dwordx4 v213, v[122:125], s[96:97] nt
	v_pk_fma_f32 v[188:189], v[4:5], v[134:135], v[130:131]
	v_pk_fma_f32 v[190:191], v[6:7], v[136:137], v[132:133]
	v_pk_fma_f32 v[192:193], v[0:1], v[204:205], v[208:209]
	v_pk_fma_f32 v[194:195], v[2:3], v[206:207], v[210:211]
	v_cndmask_b32_e64 v20, v4, v20, s[10:11]
	v_cndmask_b32_e64 v21, v5, v21, s[10:11]
	v_cndmask_b32_e64 v22, v6, v22, s[10:11]
	v_cndmask_b32_e64 v23, v7, v23, s[10:11]
	v_cndmask_b32_e64 v8, v0, v8, s[10:11]
	v_cndmask_b32_e64 v9, v1, v9, s[10:11]
	v_cndmask_b32_e64 v10, v2, v10, s[10:11]
	v_cndmask_b32_e64 v11, v3, v11, s[10:11]
	v_fmac_f32_dpp v188, v20, v154 row_ror:2 row_mask:0xf bank_mask:0xf
	v_fmac_f32_dpp v189, v21, v155 row_ror:2 row_mask:0xf bank_mask:0xf
	v_fmac_f32_dpp v190, v22, v156 row_ror:2 row_mask:0xf bank_mask:0xf
	v_fmac_f32_dpp v191, v23, v157 row_ror:2 row_mask:0xf bank_mask:0xf
	v_fmac_f32_dpp v192, v8, v118 row_ror:2 row_mask:0xf bank_mask:0xf
	v_fmac_f32_dpp v193, v9, v119 row_ror:2 row_mask:0xf bank_mask:0xf
	v_fmac_f32_dpp v194, v10, v120 row_ror:2 row_mask:0xf bank_mask:0xf
	v_fmac_f32_dpp v195, v11, v121 row_ror:2 row_mask:0xf bank_mask:0xf
	v_cndmask_b32_e64 v20, v4, v20, s[8:9]
	v_cndmask_b32_e64 v21, v5, v21, s[8:9]
	v_cndmask_b32_e64 v22, v6, v22, s[8:9]
	v_cndmask_b32_e64 v23, v7, v23, s[8:9]
	v_cndmask_b32_e64 v8, v0, v8, s[8:9]
	v_cndmask_b32_e64 v9, v1, v9, s[8:9]
	v_cndmask_b32_e64 v10, v2, v10, s[8:9]
	v_cndmask_b32_e64 v11, v3, v11, s[8:9]
	v_fmac_f32_dpp v188, v20, v142 row_ror:1 row_mask:0xf bank_mask:0xf
	v_fmac_f32_dpp v189, v21, v143 row_ror:1 row_mask:0xf bank_mask:0xf
	v_fmac_f32_dpp v190, v22, v144 row_ror:1 row_mask:0xf bank_mask:0xf
	v_fmac_f32_dpp v191, v23, v145 row_ror:1 row_mask:0xf bank_mask:0xf
	v_fmac_f32_dpp v192, v8, v110 row_ror:1 row_mask:0xf bank_mask:0xf
	v_fmac_f32_dpp v193, v9, v111 row_ror:1 row_mask:0xf bank_mask:0xf
	v_fmac_f32_dpp v194, v10, v112 row_ror:1 row_mask:0xf bank_mask:0xf
	v_fmac_f32_dpp v195, v11, v113 row_ror:1 row_mask:0xf bank_mask:0xf
	v_pk_mul_f32 v[196:197], v[188:189], v[216:217] op_sel_hi:[1,0]
	v_pk_mul_f32 v[198:199], v[190:191], v[216:217] op_sel_hi:[1,0]
	v_exp_f32_e32 v196, v196
	v_exp_f32_e32 v197, v197
	v_exp_f32_e32 v198, v198
	v_exp_f32_e32 v199, v199
	v_pk_add_f32 v[196:197], v[196:197], v[214:215] op_sel_hi:[1,0]
	v_pk_add_f32 v[198:199], v[198:199], v[214:215] op_sel_hi:[1,0]
	v_rcp_f32_e32 v196, v196
	v_rcp_f32_e32 v197, v197
	v_rcp_f32_e32 v198, v198
	v_rcp_f32_e32 v199, v199
	v_pk_mul_f32 v[188:189], v[188:189], v[196:197]
	v_pk_mul_f32 v[190:191], v[190:191], v[198:199]
	v_pk_mul_f32 v[188:189], v[188:189], v[192:193]
	v_pk_mul_f32 v[190:191], v[190:191], v[194:195]
	v_cvt_pk_bf16_f32 v116, v188, v189
	v_cvt_pk_bf16_f32 v117, v190, v191
	v_add_u32_e32 v213, 0x134000, v215
	global_store_dwordx4 v213, v[114:117], s[96:97] nt
	s_branch .LBB0_836
